# ret_proj gate-tile epilogue: silu bf16 results staged through wave-private LDS image and written as 16-byte full-row stores instead of 128 2-byte stores per thread
# speedup vs baseline: 1.0062x; 1.0012x over previous
.LBB0_1018:
	s_add_i32 s3, s1, 1
	s_cmp_lt_u32 s1, 15
	s_cselect_b32 s1, s3, s1
	s_lshl_b32 s12, s1, 6
	s_lshl_b64 s[10:11], s[12:13], 1
	s_barrier
	s_waitcnt vmcnt(0)
	ds_write_b128 v204, v[174:177]
	ds_write_b128 v204, v[170:173] offset:4608
	ds_write_b128 v204, v[166:169] offset:9216
	ds_write_b128 v204, v[162:165] offset:13824
	ds_write_b128 v204, v[158:161] offset:18432
	ds_write_b128 v204, v[154:157] offset:23040
	ds_write_b128 v204, v[150:153] offset:27648
	ds_write_b128 v204, v[146:149] offset:32256
	ds_write_b128 v204, v[142:145] offset:36864
	ds_write_b128 v204, v[134:137] offset:41472
	ds_write_b128 v204, v[130:133] offset:46080
	ds_write_b128 v204, v[138:141] offset:50688
	v_lshl_add_u64 v[130:131], v[178:179], 0, s[10:11]
	s_add_u32 s100, s10, 0x10000
	s_addc_u32 s101, s11, 0
	v_lshl_add_u64 v[132:133], v[178:179], 0, s[100:101]
	s_add_u32 s100, s100, 0x10000
	s_addc_u32 s101, s101, 0
	v_lshl_add_u64 v[134:135], v[178:179], 0, s[100:101]
	s_add_u32 s100, s100, 0x10000
	s_addc_u32 s101, s101, 0
	v_lshl_add_u64 v[136:137], v[178:179], 0, s[100:101]
	s_add_u32 s100, s100, 0x10000
	s_addc_u32 s101, s101, 0
	v_lshl_add_u64 v[138:139], v[178:179], 0, s[100:101]
	s_add_u32 s100, s100, 0x10000
	s_addc_u32 s101, s101, 0
	v_lshl_add_u64 v[140:141], v[178:179], 0, s[100:101]
	s_add_u32 s100, s100, 0x10000
	s_addc_u32 s101, s101, 0
	v_lshl_add_u64 v[142:143], v[178:179], 0, s[100:101]
	s_add_u32 s100, s100, 0x10000
	s_addc_u32 s101, s101, 0
	v_lshl_add_u64 v[144:145], v[178:179], 0, s[100:101]
	s_waitcnt lgkmcnt(0)
	s_barrier
	v_lshl_add_u64 v[224:225], v[180:181], 0, s[10:11]
	s_add_u32 s100, s10, 0x10000
	s_addc_u32 s101, s11, 0
	v_lshl_add_u64 v[226:227], v[180:181], 0, s[100:101]
	s_add_u32 s100, s100, 0x10000
	s_addc_u32 s101, s101, 0
	v_lshl_add_u64 v[228:229], v[180:181], 0, s[100:101]
	s_add_u32 s100, s100, 0x10000
	s_addc_u32 s101, s101, 0
	v_lshl_add_u64 v[230:231], v[180:181], 0, s[100:101]
	global_load_dwordx4 v[174:177], v[130:131], off
	global_load_dwordx4 v[170:173], v[132:133], off
	global_load_dwordx4 v[166:169], v[134:135], off
	global_load_dwordx4 v[162:165], v[136:137], off
	global_load_dwordx4 v[158:161], v[138:139], off
	global_load_dwordx4 v[154:157], v[140:141], off
	global_load_dwordx4 v[150:153], v[142:143], off
	global_load_dwordx4 v[146:149], v[144:145], off
	global_load_dwordx4 v[142:145], v[224:225], off
	global_load_dwordx4 v[134:137], v[226:227], off
	global_load_dwordx4 v[130:133], v[228:229], off
	global_load_dwordx4 v[138:141], v[230:231], off
	s_setprio 2
	ds_read_b128 v[224:227], v182
	ds_read_b128 v[228:231], v183 offset:36864
	ds_read_b128 v[232:235], v183 offset:41472
	ds_read_b128 v[184:187], v182 offset:4608
	ds_read_b128 v[236:239], v183 offset:46080
	ds_read_b128 v[240:243], v183 offset:50688
	s_waitcnt lgkmcnt(4)
	v_mfma_f32_32x32x16_bf16 v[114:129], v[224:227], v[228:231], v[114:129]
	ds_read_b128 v[188:191], v183 offset:36896
	ds_read_b128 v[192:195], v183 offset:41504
	s_waitcnt lgkmcnt(5)
	v_mfma_f32_32x32x16_bf16 v[82:97], v[224:227], v[232:235], v[82:97]
	ds_read_b128 v[196:199], v183 offset:46112
	ds_read_b128 v[200:203], v183 offset:50720
	s_waitcnt lgkmcnt(5)
	v_mfma_f32_32x32x16_bf16 v[98:113], v[224:227], v[236:239], v[98:113]
	s_waitcnt lgkmcnt(4)
	v_mfma_f32_32x32x16_bf16 v[66:81], v[224:227], v[240:243], v[66:81]
	ds_read_b128 v[224:227], v182 offset:32
	v_mfma_f32_32x32x16_bf16 v[50:65], v[184:187], v[228:231], v[50:65]
	v_mfma_f32_32x32x16_bf16 v[16:31], v[184:187], v[232:235], v[16:31]
	v_mfma_f32_32x32x16_bf16 v[34:49], v[184:187], v[236:239], v[34:49]
	v_mfma_f32_32x32x16_bf16 v[0:15], v[184:187], v[240:243], v[0:15]
	ds_read_b128 v[184:187], v182 offset:4640
	s_waitcnt lgkmcnt(1)
	v_mfma_f32_32x32x16_bf16 v[114:129], v[224:227], v[188:191], v[114:129]
	ds_read_b128 v[228:231], v183 offset:36928
	ds_read_b128 v[232:235], v183 offset:41536
	v_mfma_f32_32x32x16_bf16 v[82:97], v[224:227], v[192:195], v[82:97]
	ds_read_b128 v[236:239], v183 offset:46144
	ds_read_b128 v[240:243], v183 offset:50752
	v_mfma_f32_32x32x16_bf16 v[98:113], v[224:227], v[196:199], v[98:113]
	v_mfma_f32_32x32x16_bf16 v[66:81], v[224:227], v[200:203], v[66:81]
	ds_read_b128 v[224:227], v182 offset:64
	s_waitcnt lgkmcnt(5)
	v_mfma_f32_32x32x16_bf16 v[50:65], v[184:187], v[188:191], v[50:65]
	v_mfma_f32_32x32x16_bf16 v[16:31], v[184:187], v[192:195], v[16:31]
	v_mfma_f32_32x32x16_bf16 v[34:49], v[184:187], v[196:199], v[34:49]
	v_mfma_f32_32x32x16_bf16 v[0:15], v[184:187], v[200:203], v[0:15]
	ds_read_b128 v[184:187], v182 offset:4672
	s_waitcnt lgkmcnt(1)
	v_mfma_f32_32x32x16_bf16 v[114:129], v[224:227], v[228:231], v[114:129]
	ds_read_b128 v[188:191], v183 offset:36960
	ds_read_b128 v[192:195], v183 offset:41568
	v_mfma_f32_32x32x16_bf16 v[82:97], v[224:227], v[232:235], v[82:97]
	ds_read_b128 v[196:199], v183 offset:46176
	ds_read_b128 v[200:203], v183 offset:50784
	v_mfma_f32_32x32x16_bf16 v[98:113], v[224:227], v[236:239], v[98:113]
	v_mfma_f32_32x32x16_bf16 v[66:81], v[224:227], v[240:243], v[66:81]
	ds_read_b128 v[224:227], v182 offset:96
	s_waitcnt lgkmcnt(5)
	v_mfma_f32_32x32x16_bf16 v[50:65], v[184:187], v[228:231], v[50:65]
	v_mfma_f32_32x32x16_bf16 v[16:31], v[184:187], v[232:235], v[16:31]
	v_mfma_f32_32x32x16_bf16 v[34:49], v[184:187], v[236:239], v[34:49]
	v_mfma_f32_32x32x16_bf16 v[0:15], v[184:187], v[240:243], v[0:15]
	ds_read_b128 v[184:187], v182 offset:4704
	s_waitcnt lgkmcnt(1)
	v_mfma_f32_32x32x16_bf16 v[114:129], v[224:227], v[188:191], v[114:129]
	v_mfma_f32_32x32x16_bf16 v[82:97], v[224:227], v[192:195], v[82:97]
	v_mfma_f32_32x32x16_bf16 v[98:113], v[224:227], v[196:199], v[98:113]
	v_mfma_f32_32x32x16_bf16 v[66:81], v[224:227], v[200:203], v[66:81]
	s_waitcnt lgkmcnt(0)
	v_mfma_f32_32x32x16_bf16 v[50:65], v[184:187], v[188:191], v[50:65]
	v_mfma_f32_32x32x16_bf16 v[16:31], v[184:187], v[192:195], v[16:31]
	v_mfma_f32_32x32x16_bf16 v[34:49], v[184:187], v[196:199], v[34:49]
	v_mfma_f32_32x32x16_bf16 v[0:15], v[184:187], v[200:203], v[0:15]
	s_setprio 0
	s_mov_b32 s1, s3
	s_cmp_lg_u32 s3, 16
	s_cbranch_scc1 .LBB0_1018
	s_lshl_b32 s1, s2, 8
	s_bfe_i32 s2, s2, 0x10017
	s_lshr_b32 s2, s2, 19
	v_writelane_b32 v251, s12, 29
	s_add_i32 s2, s1, s2
	s_and_b32 s2, s2, 0xffffe000
	v_writelane_b32 v251, s13, 30
	s_ashr_i32 s12, s8, 8
	s_add_i32 s12, s12, s9
	s_sub_i32 s17, s1, s2
	s_cmp_gt_i32 s0, 15
	s_mov_b64 s[2:3], -1
	s_barrier
	s_cbranch_scc0 .LBB0_1025
	s_cmp_gt_u32 s0, 31
	s_cbranch_scc0 .LBB0_1022
	v_mov_b32_e32 v32, v206
	v_readlane_b32 s24, v249, 18
	s_waitcnt vmcnt(1)
	v_and_b32_e32 v130, 0xffffffc0, v32
	v_lshrrev_b32_e32 v131, 3, v32
	v_and_or_b32 v130, v131, 4, v130
	v_add_u32_e32 v132, s1, v130
	s_lshl_b32 s1, s0, 8
	v_readlane_b32 s26, v249, 20
	v_and_b32_e32 v32, 31, v32
	v_readlane_b32 s27, v249, 21
	s_add_u32 s2, s26, s1
	s_addc_u32 s3, s27, 0
	v_lshlrev_b32_e32 v32, 1, v32
	v_lshl_add_u64 v[130:131], s[2:3], 0, v[32:33]
	s_movk_i32 s2, 0xe000
	s_mov_b32 s3, -1
	v_lshl_add_u64 v[130:131], v[130:131], 0, s[2:3]
	v_ashrrev_i32_e32 v133, 31, v132
	s_movk_i32 s1, 0x7fff
	v_readlane_b32 s25, v249, 19
	s_waitcnt vmcnt(0)
	v_readlane_b32 s28, v249, 22
	v_readlane_b32 s29, v249, 23
	v_readlane_b32 s30, v249, 24
	v_readlane_b32 s31, v249, 25
	v_ashrrev_i32_e32 v133, 31, v132
	v_lshrrev_b32_e32 v149, 6, v206
	v_and_b32_e32 v150, 63, v206
	v_mul_u32_u24_e32 v146, 0x2200, v149
	v_lshrrev_b32_e32 v151, 5, v150
	v_and_b32_e32 v152, 31, v150
	v_mul_u32_u24_e32 v147, 0x440, v151
	v_lshl_add_u32 v147, v152, 1, v147
	v_add_u32_e32 v147, v147, v146
	v_lshrrev_b32_e32 v149, 4, v150
	v_and_b32_e32 v150, 15, v150
	v_mul_u32_u24_e32 v148, 0x110, v149
	v_lshl_add_u32 v148, v150, 4, v148
	v_add_u32_e32 v148, v148, v146
	v_lshlrev_b32_e32 v151, 2, v151
	v_sub_u32_e32 v154, v132, v151
	v_add_u32_e32 v154, v154, v149
	v_ashrrev_i32_e32 v155, 31, v154
	v_lshlrev_b64 v[154:155], 12, v[154:155]
	v_lshlrev_b32_e32 v150, 4, v150
	v_lshlrev_b32_e32 v152, 1, v152
	v_sub_u32_e32 v156, v150, v152
	v_ashrrev_i32_e32 v157, 31, v156
	v_lshl_add_u64 v[158:159], v[130:131], 0, v[154:155]
	v_lshl_add_u64 v[158:159], v[158:159], 0, v[156:157]
	s_mov_b64 s[100:101], 0x4000
	v_mul_f32_e32 v134, 0xbfb8aa3b, v114
	v_mul_f32_e32 v140, 0xbfb8aa3b, v98
	v_exp_f32_e32 v134, v134
	v_exp_f32_e32 v140, v140
	v_add_f32_e32 v134, 1.0, v134
	v_add_f32_e32 v140, 1.0, v140
	v_div_scale_f32 v135, s[2:3], v134, v134, v114
	v_div_scale_f32 v141, s[2:3], v140, v140, v98
	v_rcp_f32_e32 v136, v135
	v_rcp_f32_e32 v142, v141
	v_fma_f32 v137, -v135, v136, 1.0
	v_fma_f32 v143, -v141, v142, 1.0
	v_fmac_f32_e32 v136, v137, v136
	v_fmac_f32_e32 v142, v143, v142
	v_div_scale_f32 v138, vcc, v114, v134, v114
	v_mul_f32_e32 v139, v138, v136
	v_fma_f32 v137, -v135, v139, v138
	v_fmac_f32_e32 v139, v137, v136
	v_fma_f32 v135, -v135, v139, v138
	v_div_fmas_f32 v135, v135, v136, v139
	v_div_scale_f32 v144, vcc, v98, v140, v98
	v_mul_f32_e32 v145, v144, v142
	v_fma_f32 v143, -v141, v145, v144
	v_fmac_f32_e32 v145, v143, v142
	v_fma_f32 v141, -v141, v145, v144
	v_div_fmas_f32 v141, v141, v142, v145
	v_div_fixup_f32 v134, v135, v134, v114
	v_div_fixup_f32 v140, v141, v140, v98
	v_bfe_u32 v135, v134, 16, 1
	v_bfe_u32 v141, v140, 16, 1
	v_add3_u32 v134, v134, v135, s1
	v_add3_u32 v140, v140, v141, s1
	ds_write_b16_d16_hi v147, v134 offset:0
	ds_write_b16_d16_hi v147, v140 offset:128
	v_mul_f32_e32 v134, 0xbfb8aa3b, v115
	v_mul_f32_e32 v140, 0xbfb8aa3b, v99
	v_exp_f32_e32 v134, v134
	v_exp_f32_e32 v140, v140
	v_add_f32_e32 v134, 1.0, v134
	v_add_f32_e32 v140, 1.0, v140
	v_div_scale_f32 v135, s[2:3], v134, v134, v115
	v_div_scale_f32 v141, s[2:3], v140, v140, v99
	v_rcp_f32_e32 v136, v135
	v_rcp_f32_e32 v142, v141
	v_fma_f32 v137, -v135, v136, 1.0
	v_fma_f32 v143, -v141, v142, 1.0
	v_fmac_f32_e32 v136, v137, v136
	v_fmac_f32_e32 v142, v143, v142
	v_div_scale_f32 v138, vcc, v115, v134, v115
	v_mul_f32_e32 v139, v138, v136
	v_fma_f32 v137, -v135, v139, v138
	v_fmac_f32_e32 v139, v137, v136
	v_fma_f32 v135, -v135, v139, v138
	v_div_fmas_f32 v135, v135, v136, v139
	v_div_scale_f32 v144, vcc, v99, v140, v99
	v_mul_f32_e32 v145, v144, v142
	v_fma_f32 v143, -v141, v145, v144
	v_fmac_f32_e32 v145, v143, v142
	v_fma_f32 v141, -v141, v145, v144
	v_div_fmas_f32 v141, v141, v142, v145
	v_div_fixup_f32 v134, v135, v134, v115
	v_div_fixup_f32 v140, v141, v140, v99
	v_bfe_u32 v135, v134, 16, 1
	v_bfe_u32 v141, v140, 16, 1
	v_add3_u32 v134, v134, v135, s1
	v_add3_u32 v140, v140, v141, s1
	ds_write_b16_d16_hi v147, v134 offset:272
	ds_write_b16_d16_hi v147, v140 offset:400
	v_mul_f32_e32 v134, 0xbfb8aa3b, v116
	v_mul_f32_e32 v140, 0xbfb8aa3b, v100
	v_exp_f32_e32 v134, v134
	v_exp_f32_e32 v140, v140
	v_add_f32_e32 v134, 1.0, v134
	v_add_f32_e32 v140, 1.0, v140
	v_div_scale_f32 v135, s[2:3], v134, v134, v116
	v_div_scale_f32 v141, s[2:3], v140, v140, v100
	v_rcp_f32_e32 v136, v135
	v_rcp_f32_e32 v142, v141
	v_fma_f32 v137, -v135, v136, 1.0
	v_fma_f32 v143, -v141, v142, 1.0
	v_fmac_f32_e32 v136, v137, v136
	v_fmac_f32_e32 v142, v143, v142
	v_div_scale_f32 v138, vcc, v116, v134, v116
	v_mul_f32_e32 v139, v138, v136
	v_fma_f32 v137, -v135, v139, v138
	v_fmac_f32_e32 v139, v137, v136
	v_fma_f32 v135, -v135, v139, v138
	v_div_fmas_f32 v135, v135, v136, v139
	v_div_scale_f32 v144, vcc, v100, v140, v100
	v_mul_f32_e32 v145, v144, v142
	v_fma_f32 v143, -v141, v145, v144
	v_fmac_f32_e32 v145, v143, v142
	v_fma_f32 v141, -v141, v145, v144
	v_div_fmas_f32 v141, v141, v142, v145
	v_div_fixup_f32 v134, v135, v134, v116
	v_div_fixup_f32 v140, v141, v140, v100
	v_bfe_u32 v135, v134, 16, 1
	v_bfe_u32 v141, v140, 16, 1
	v_add3_u32 v134, v134, v135, s1
	v_add3_u32 v140, v140, v141, s1
	ds_write_b16_d16_hi v147, v134 offset:544
	ds_write_b16_d16_hi v147, v140 offset:672
	v_mul_f32_e32 v134, 0xbfb8aa3b, v117
	v_mul_f32_e32 v140, 0xbfb8aa3b, v101
	v_exp_f32_e32 v134, v134
	v_exp_f32_e32 v140, v140
	v_add_f32_e32 v134, 1.0, v134
	v_add_f32_e32 v140, 1.0, v140
	v_div_scale_f32 v135, s[2:3], v134, v134, v117
	v_div_scale_f32 v141, s[2:3], v140, v140, v101
	v_rcp_f32_e32 v136, v135
	v_rcp_f32_e32 v142, v141
	v_fma_f32 v137, -v135, v136, 1.0
	v_fma_f32 v143, -v141, v142, 1.0
	v_fmac_f32_e32 v136, v137, v136
	v_fmac_f32_e32 v142, v143, v142
	v_div_scale_f32 v138, vcc, v117, v134, v117
	v_mul_f32_e32 v139, v138, v136
	v_fma_f32 v137, -v135, v139, v138
	v_fmac_f32_e32 v139, v137, v136
	v_fma_f32 v135, -v135, v139, v138
	v_div_fmas_f32 v135, v135, v136, v139
	v_div_scale_f32 v144, vcc, v101, v140, v101
	v_mul_f32_e32 v145, v144, v142
	v_fma_f32 v143, -v141, v145, v144
	v_fmac_f32_e32 v145, v143, v142
	v_fma_f32 v141, -v141, v145, v144
	v_div_fmas_f32 v141, v141, v142, v145
	v_div_fixup_f32 v134, v135, v134, v117
	v_div_fixup_f32 v140, v141, v140, v101
	v_bfe_u32 v135, v134, 16, 1
	v_bfe_u32 v141, v140, 16, 1
	v_add3_u32 v134, v134, v135, s1
	v_add3_u32 v140, v140, v141, s1
	ds_write_b16_d16_hi v147, v134 offset:816
	ds_write_b16_d16_hi v147, v140 offset:944
	v_mul_f32_e32 v134, 0xbfb8aa3b, v118
	v_mul_f32_e32 v140, 0xbfb8aa3b, v102
	v_exp_f32_e32 v134, v134
	v_exp_f32_e32 v140, v140
	v_add_f32_e32 v134, 1.0, v134
	v_add_f32_e32 v140, 1.0, v140
	v_div_scale_f32 v135, s[2:3], v134, v134, v118
	v_div_scale_f32 v141, s[2:3], v140, v140, v102
	v_rcp_f32_e32 v136, v135
	v_rcp_f32_e32 v142, v141
	v_fma_f32 v137, -v135, v136, 1.0
	v_fma_f32 v143, -v141, v142, 1.0
	v_fmac_f32_e32 v136, v137, v136
	v_fmac_f32_e32 v142, v143, v142
	v_div_scale_f32 v138, vcc, v118, v134, v118
	v_mul_f32_e32 v139, v138, v136
	v_fma_f32 v137, -v135, v139, v138
	v_fmac_f32_e32 v139, v137, v136
	v_fma_f32 v135, -v135, v139, v138
	v_div_fmas_f32 v135, v135, v136, v139
	v_div_scale_f32 v144, vcc, v102, v140, v102
	v_mul_f32_e32 v145, v144, v142
	v_fma_f32 v143, -v141, v145, v144
	v_fmac_f32_e32 v145, v143, v142
	v_fma_f32 v141, -v141, v145, v144
	v_div_fmas_f32 v141, v141, v142, v145
	v_div_fixup_f32 v134, v135, v134, v118
	v_div_fixup_f32 v140, v141, v140, v102
	v_bfe_u32 v135, v134, 16, 1
	v_bfe_u32 v141, v140, 16, 1
	v_add3_u32 v134, v134, v135, s1
	v_add3_u32 v140, v140, v141, s1
	ds_write_b16_d16_hi v147, v134 offset:2176
	ds_write_b16_d16_hi v147, v140 offset:2304
	v_mul_f32_e32 v134, 0xbfb8aa3b, v119
	v_mul_f32_e32 v140, 0xbfb8aa3b, v103
	v_exp_f32_e32 v134, v134
	v_exp_f32_e32 v140, v140
	v_add_f32_e32 v134, 1.0, v134
	v_add_f32_e32 v140, 1.0, v140
	v_div_scale_f32 v135, s[2:3], v134, v134, v119
	v_div_scale_f32 v141, s[2:3], v140, v140, v103
	v_rcp_f32_e32 v136, v135
	v_rcp_f32_e32 v142, v141
	v_fma_f32 v137, -v135, v136, 1.0
	v_fma_f32 v143, -v141, v142, 1.0
	v_fmac_f32_e32 v136, v137, v136
	v_fmac_f32_e32 v142, v143, v142
	v_div_scale_f32 v138, vcc, v119, v134, v119
	v_mul_f32_e32 v139, v138, v136
	v_fma_f32 v137, -v135, v139, v138
	v_fmac_f32_e32 v139, v137, v136
	v_fma_f32 v135, -v135, v139, v138
	v_div_fmas_f32 v135, v135, v136, v139
	v_div_scale_f32 v144, vcc, v103, v140, v103
	v_mul_f32_e32 v145, v144, v142
	v_fma_f32 v143, -v141, v145, v144
	v_fmac_f32_e32 v145, v143, v142
	v_fma_f32 v141, -v141, v145, v144
	v_div_fmas_f32 v141, v141, v142, v145
	v_div_fixup_f32 v134, v135, v134, v119
	v_div_fixup_f32 v140, v141, v140, v103
	v_bfe_u32 v135, v134, 16, 1
	v_bfe_u32 v141, v140, 16, 1
	v_add3_u32 v134, v134, v135, s1
	v_add3_u32 v140, v140, v141, s1
	ds_write_b16_d16_hi v147, v134 offset:2448
	ds_write_b16_d16_hi v147, v140 offset:2576
	v_mul_f32_e32 v134, 0xbfb8aa3b, v120
	v_mul_f32_e32 v140, 0xbfb8aa3b, v104
	v_exp_f32_e32 v134, v134
	v_exp_f32_e32 v140, v140
	v_add_f32_e32 v134, 1.0, v134
	v_add_f32_e32 v140, 1.0, v140
	v_div_scale_f32 v135, s[2:3], v134, v134, v120
	v_div_scale_f32 v141, s[2:3], v140, v140, v104
	v_rcp_f32_e32 v136, v135
	v_rcp_f32_e32 v142, v141
	v_fma_f32 v137, -v135, v136, 1.0
	v_fma_f32 v143, -v141, v142, 1.0
	v_fmac_f32_e32 v136, v137, v136
	v_fmac_f32_e32 v142, v143, v142
	v_div_scale_f32 v138, vcc, v120, v134, v120
	v_mul_f32_e32 v139, v138, v136
	v_fma_f32 v137, -v135, v139, v138
	v_fmac_f32_e32 v139, v137, v136
	v_fma_f32 v135, -v135, v139, v138
	v_div_fmas_f32 v135, v135, v136, v139
	v_div_scale_f32 v144, vcc, v104, v140, v104
	v_mul_f32_e32 v145, v144, v142
	v_fma_f32 v143, -v141, v145, v144
	v_fmac_f32_e32 v145, v143, v142
	v_fma_f32 v141, -v141, v145, v144
	v_div_fmas_f32 v141, v141, v142, v145
	v_div_fixup_f32 v134, v135, v134, v120
	v_div_fixup_f32 v140, v141, v140, v104
	v_bfe_u32 v135, v134, 16, 1
	v_bfe_u32 v141, v140, 16, 1
	v_add3_u32 v134, v134, v135, s1
	v_add3_u32 v140, v140, v141, s1
	ds_write_b16_d16_hi v147, v134 offset:2720
	ds_write_b16_d16_hi v147, v140 offset:2848
	v_mul_f32_e32 v134, 0xbfb8aa3b, v121
	v_mul_f32_e32 v140, 0xbfb8aa3b, v105
	v_exp_f32_e32 v134, v134
	v_exp_f32_e32 v140, v140
	v_add_f32_e32 v134, 1.0, v134
	v_add_f32_e32 v140, 1.0, v140
	v_div_scale_f32 v135, s[2:3], v134, v134, v121
	v_div_scale_f32 v141, s[2:3], v140, v140, v105
	v_rcp_f32_e32 v136, v135
	v_rcp_f32_e32 v142, v141
	v_fma_f32 v137, -v135, v136, 1.0
	v_fma_f32 v143, -v141, v142, 1.0
	v_fmac_f32_e32 v136, v137, v136
	v_fmac_f32_e32 v142, v143, v142
	v_div_scale_f32 v138, vcc, v121, v134, v121
	v_mul_f32_e32 v139, v138, v136
	v_fma_f32 v137, -v135, v139, v138
	v_fmac_f32_e32 v139, v137, v136
	v_fma_f32 v135, -v135, v139, v138
	v_div_fmas_f32 v135, v135, v136, v139
	v_div_scale_f32 v144, vcc, v105, v140, v105
	v_mul_f32_e32 v145, v144, v142
	v_fma_f32 v143, -v141, v145, v144
	v_fmac_f32_e32 v145, v143, v142
	v_fma_f32 v141, -v141, v145, v144
	v_div_fmas_f32 v141, v141, v142, v145
	v_div_fixup_f32 v134, v135, v134, v121
	v_div_fixup_f32 v140, v141, v140, v105
	v_bfe_u32 v135, v134, 16, 1
	v_bfe_u32 v141, v140, 16, 1
	v_add3_u32 v134, v134, v135, s1
	v_add3_u32 v140, v140, v141, s1
	ds_write_b16_d16_hi v147, v134 offset:2992
	ds_write_b16_d16_hi v147, v140 offset:3120
	v_mul_f32_e32 v134, 0xbfb8aa3b, v122
	v_mul_f32_e32 v140, 0xbfb8aa3b, v106
	v_exp_f32_e32 v134, v134
	v_exp_f32_e32 v140, v140
	v_add_f32_e32 v134, 1.0, v134
	v_add_f32_e32 v140, 1.0, v140
	v_div_scale_f32 v135, s[2:3], v134, v134, v122
	v_div_scale_f32 v141, s[2:3], v140, v140, v106
	v_rcp_f32_e32 v136, v135
	v_rcp_f32_e32 v142, v141
	v_fma_f32 v137, -v135, v136, 1.0
	v_fma_f32 v143, -v141, v142, 1.0
	v_fmac_f32_e32 v136, v137, v136
	v_fmac_f32_e32 v142, v143, v142
	v_div_scale_f32 v138, vcc, v122, v134, v122
	v_mul_f32_e32 v139, v138, v136
	v_fma_f32 v137, -v135, v139, v138
	v_fmac_f32_e32 v139, v137, v136
	v_fma_f32 v135, -v135, v139, v138
	v_div_fmas_f32 v135, v135, v136, v139
	v_div_scale_f32 v144, vcc, v106, v140, v106
	v_mul_f32_e32 v145, v144, v142
	v_fma_f32 v143, -v141, v145, v144
	v_fmac_f32_e32 v145, v143, v142
	v_fma_f32 v141, -v141, v145, v144
	v_div_fmas_f32 v141, v141, v142, v145
	v_div_fixup_f32 v134, v135, v134, v122
	v_div_fixup_f32 v140, v141, v140, v106
	v_bfe_u32 v135, v134, 16, 1
	v_bfe_u32 v141, v140, 16, 1
	v_add3_u32 v134, v134, v135, s1
	v_add3_u32 v140, v140, v141, s1
	ds_write_b16_d16_hi v147, v134 offset:4352
	ds_write_b16_d16_hi v147, v140 offset:4480
	v_mul_f32_e32 v134, 0xbfb8aa3b, v123
	v_mul_f32_e32 v140, 0xbfb8aa3b, v107
	v_exp_f32_e32 v134, v134
	v_exp_f32_e32 v140, v140
	v_add_f32_e32 v134, 1.0, v134
	v_add_f32_e32 v140, 1.0, v140
	v_div_scale_f32 v135, s[2:3], v134, v134, v123
	v_div_scale_f32 v141, s[2:3], v140, v140, v107
	v_rcp_f32_e32 v136, v135
	v_rcp_f32_e32 v142, v141
	v_fma_f32 v137, -v135, v136, 1.0
	v_fma_f32 v143, -v141, v142, 1.0
	v_fmac_f32_e32 v136, v137, v136
	v_fmac_f32_e32 v142, v143, v142
	v_div_scale_f32 v138, vcc, v123, v134, v123
	v_mul_f32_e32 v139, v138, v136
	v_fma_f32 v137, -v135, v139, v138
	v_fmac_f32_e32 v139, v137, v136
	v_fma_f32 v135, -v135, v139, v138
	v_div_fmas_f32 v135, v135, v136, v139
	v_div_scale_f32 v144, vcc, v107, v140, v107
	v_mul_f32_e32 v145, v144, v142
	v_fma_f32 v143, -v141, v145, v144
	v_fmac_f32_e32 v145, v143, v142
	v_fma_f32 v141, -v141, v145, v144
	v_div_fmas_f32 v141, v141, v142, v145
	v_div_fixup_f32 v134, v135, v134, v123
	v_div_fixup_f32 v140, v141, v140, v107
	v_bfe_u32 v135, v134, 16, 1
	v_bfe_u32 v141, v140, 16, 1
	v_add3_u32 v134, v134, v135, s1
	v_add3_u32 v140, v140, v141, s1
	ds_write_b16_d16_hi v147, v134 offset:4624
	ds_write_b16_d16_hi v147, v140 offset:4752
	v_mul_f32_e32 v134, 0xbfb8aa3b, v124
	v_mul_f32_e32 v140, 0xbfb8aa3b, v108
	v_exp_f32_e32 v134, v134
	v_exp_f32_e32 v140, v140
	v_add_f32_e32 v134, 1.0, v134
	v_add_f32_e32 v140, 1.0, v140
	v_div_scale_f32 v135, s[2:3], v134, v134, v124
	v_div_scale_f32 v141, s[2:3], v140, v140, v108
	v_rcp_f32_e32 v136, v135
	v_rcp_f32_e32 v142, v141
	v_fma_f32 v137, -v135, v136, 1.0
	v_fma_f32 v143, -v141, v142, 1.0
	v_fmac_f32_e32 v136, v137, v136
	v_fmac_f32_e32 v142, v143, v142
	v_div_scale_f32 v138, vcc, v124, v134, v124
	v_mul_f32_e32 v139, v138, v136
	v_fma_f32 v137, -v135, v139, v138
	v_fmac_f32_e32 v139, v137, v136
	v_fma_f32 v135, -v135, v139, v138
	v_div_fmas_f32 v135, v135, v136, v139
	v_div_scale_f32 v144, vcc, v108, v140, v108
	v_mul_f32_e32 v145, v144, v142
	v_fma_f32 v143, -v141, v145, v144
	v_fmac_f32_e32 v145, v143, v142
	v_fma_f32 v141, -v141, v145, v144
	v_div_fmas_f32 v141, v141, v142, v145
	v_div_fixup_f32 v134, v135, v134, v124
	v_div_fixup_f32 v140, v141, v140, v108
	v_bfe_u32 v135, v134, 16, 1
	v_bfe_u32 v141, v140, 16, 1
	v_add3_u32 v134, v134, v135, s1
	v_add3_u32 v140, v140, v141, s1
	ds_write_b16_d16_hi v147, v134 offset:4896
	ds_write_b16_d16_hi v147, v140 offset:5024
	v_mul_f32_e32 v134, 0xbfb8aa3b, v125
	v_mul_f32_e32 v140, 0xbfb8aa3b, v109
	v_exp_f32_e32 v134, v134
	v_exp_f32_e32 v140, v140
	v_add_f32_e32 v134, 1.0, v134
	v_add_f32_e32 v140, 1.0, v140
	v_div_scale_f32 v135, s[2:3], v134, v134, v125
	v_div_scale_f32 v141, s[2:3], v140, v140, v109
	v_rcp_f32_e32 v136, v135
	v_rcp_f32_e32 v142, v141
	v_fma_f32 v137, -v135, v136, 1.0
	v_fma_f32 v143, -v141, v142, 1.0
	v_fmac_f32_e32 v136, v137, v136
	v_fmac_f32_e32 v142, v143, v142
	v_div_scale_f32 v138, vcc, v125, v134, v125
	v_mul_f32_e32 v139, v138, v136
	v_fma_f32 v137, -v135, v139, v138
	v_fmac_f32_e32 v139, v137, v136
	v_fma_f32 v135, -v135, v139, v138
	v_div_fmas_f32 v135, v135, v136, v139
	v_div_scale_f32 v144, vcc, v109, v140, v109
	v_mul_f32_e32 v145, v144, v142
	v_fma_f32 v143, -v141, v145, v144
	v_fmac_f32_e32 v145, v143, v142
	v_fma_f32 v141, -v141, v145, v144
	v_div_fmas_f32 v141, v141, v142, v145
	v_div_fixup_f32 v134, v135, v134, v125
	v_div_fixup_f32 v140, v141, v140, v109
	v_bfe_u32 v135, v134, 16, 1
	v_bfe_u32 v141, v140, 16, 1
	v_add3_u32 v134, v134, v135, s1
	v_add3_u32 v140, v140, v141, s1
	ds_write_b16_d16_hi v147, v134 offset:5168
	ds_write_b16_d16_hi v147, v140 offset:5296
	v_mul_f32_e32 v134, 0xbfb8aa3b, v126
	v_mul_f32_e32 v140, 0xbfb8aa3b, v110
	v_exp_f32_e32 v134, v134
	v_exp_f32_e32 v140, v140
	v_add_f32_e32 v134, 1.0, v134
	v_add_f32_e32 v140, 1.0, v140
	v_div_scale_f32 v135, s[2:3], v134, v134, v126
	v_div_scale_f32 v141, s[2:3], v140, v140, v110
	v_rcp_f32_e32 v136, v135
	v_rcp_f32_e32 v142, v141
	v_fma_f32 v137, -v135, v136, 1.0
	v_fma_f32 v143, -v141, v142, 1.0
	v_fmac_f32_e32 v136, v137, v136
	v_fmac_f32_e32 v142, v143, v142
	v_div_scale_f32 v138, vcc, v126, v134, v126
	v_mul_f32_e32 v139, v138, v136
	v_fma_f32 v137, -v135, v139, v138
	v_fmac_f32_e32 v139, v137, v136
	v_fma_f32 v135, -v135, v139, v138
	v_div_fmas_f32 v135, v135, v136, v139
	v_div_scale_f32 v144, vcc, v110, v140, v110
	v_mul_f32_e32 v145, v144, v142
	v_fma_f32 v143, -v141, v145, v144
	v_fmac_f32_e32 v145, v143, v142
	v_fma_f32 v141, -v141, v145, v144
	v_div_fmas_f32 v141, v141, v142, v145
	v_div_fixup_f32 v134, v135, v134, v126
	v_div_fixup_f32 v140, v141, v140, v110
	v_bfe_u32 v135, v134, 16, 1
	v_bfe_u32 v141, v140, 16, 1
	v_add3_u32 v134, v134, v135, s1
	v_add3_u32 v140, v140, v141, s1
	ds_write_b16_d16_hi v147, v134 offset:6528
	ds_write_b16_d16_hi v147, v140 offset:6656
	v_mul_f32_e32 v134, 0xbfb8aa3b, v127
	v_mul_f32_e32 v140, 0xbfb8aa3b, v111
	v_exp_f32_e32 v134, v134
	v_exp_f32_e32 v140, v140
	v_add_f32_e32 v134, 1.0, v134
	v_add_f32_e32 v140, 1.0, v140
	v_div_scale_f32 v135, s[2:3], v134, v134, v127
	v_div_scale_f32 v141, s[2:3], v140, v140, v111
	v_rcp_f32_e32 v136, v135
	v_rcp_f32_e32 v142, v141
	v_fma_f32 v137, -v135, v136, 1.0
	v_fma_f32 v143, -v141, v142, 1.0
	v_fmac_f32_e32 v136, v137, v136
	v_fmac_f32_e32 v142, v143, v142
	v_div_scale_f32 v138, vcc, v127, v134, v127
	v_mul_f32_e32 v139, v138, v136
	v_fma_f32 v137, -v135, v139, v138
	v_fmac_f32_e32 v139, v137, v136
	v_fma_f32 v135, -v135, v139, v138
	v_div_fmas_f32 v135, v135, v136, v139
	v_div_scale_f32 v144, vcc, v111, v140, v111
	v_mul_f32_e32 v145, v144, v142
	v_fma_f32 v143, -v141, v145, v144
	v_fmac_f32_e32 v145, v143, v142
	v_fma_f32 v141, -v141, v145, v144
	v_div_fmas_f32 v141, v141, v142, v145
	v_div_fixup_f32 v134, v135, v134, v127
	v_div_fixup_f32 v140, v141, v140, v111
	v_bfe_u32 v135, v134, 16, 1
	v_bfe_u32 v141, v140, 16, 1
	v_add3_u32 v134, v134, v135, s1
	v_add3_u32 v140, v140, v141, s1
	ds_write_b16_d16_hi v147, v134 offset:6800
	ds_write_b16_d16_hi v147, v140 offset:6928
	v_mul_f32_e32 v134, 0xbfb8aa3b, v128
	v_mul_f32_e32 v140, 0xbfb8aa3b, v112
	v_exp_f32_e32 v134, v134
	v_exp_f32_e32 v140, v140
	v_add_f32_e32 v134, 1.0, v134
	v_add_f32_e32 v140, 1.0, v140
	v_div_scale_f32 v135, s[2:3], v134, v134, v128
	v_div_scale_f32 v141, s[2:3], v140, v140, v112
	v_rcp_f32_e32 v136, v135
	v_rcp_f32_e32 v142, v141
	v_fma_f32 v137, -v135, v136, 1.0
	v_fma_f32 v143, -v141, v142, 1.0
	v_fmac_f32_e32 v136, v137, v136
	v_fmac_f32_e32 v142, v143, v142
	v_div_scale_f32 v138, vcc, v128, v134, v128
	v_mul_f32_e32 v139, v138, v136
	v_fma_f32 v137, -v135, v139, v138
	v_fmac_f32_e32 v139, v137, v136
	v_fma_f32 v135, -v135, v139, v138
	v_div_fmas_f32 v135, v135, v136, v139
	v_div_scale_f32 v144, vcc, v112, v140, v112
	v_mul_f32_e32 v145, v144, v142
	v_fma_f32 v143, -v141, v145, v144
	v_fmac_f32_e32 v145, v143, v142
	v_fma_f32 v141, -v141, v145, v144
	v_div_fmas_f32 v141, v141, v142, v145
	v_div_fixup_f32 v134, v135, v134, v128
	v_div_fixup_f32 v140, v141, v140, v112
	v_bfe_u32 v135, v134, 16, 1
	v_bfe_u32 v141, v140, 16, 1
	v_add3_u32 v134, v134, v135, s1
	v_add3_u32 v140, v140, v141, s1
	ds_write_b16_d16_hi v147, v134 offset:7072
	ds_write_b16_d16_hi v147, v140 offset:7200
	v_mul_f32_e32 v134, 0xbfb8aa3b, v129
	v_mul_f32_e32 v140, 0xbfb8aa3b, v113
	v_exp_f32_e32 v134, v134
	v_exp_f32_e32 v140, v140
	v_add_f32_e32 v134, 1.0, v134
	v_add_f32_e32 v140, 1.0, v140
	v_div_scale_f32 v135, s[2:3], v134, v134, v129
	v_div_scale_f32 v141, s[2:3], v140, v140, v113
	v_rcp_f32_e32 v136, v135
	v_rcp_f32_e32 v142, v141
	v_fma_f32 v137, -v135, v136, 1.0
	v_fma_f32 v143, -v141, v142, 1.0
	v_fmac_f32_e32 v136, v137, v136
	v_fmac_f32_e32 v142, v143, v142
	v_div_scale_f32 v138, vcc, v129, v134, v129
	v_mul_f32_e32 v139, v138, v136
	v_fma_f32 v137, -v135, v139, v138
	v_fmac_f32_e32 v139, v137, v136
	v_fma_f32 v135, -v135, v139, v138
	v_div_fmas_f32 v135, v135, v136, v139
	v_div_scale_f32 v144, vcc, v113, v140, v113
	v_mul_f32_e32 v145, v144, v142
	v_fma_f32 v143, -v141, v145, v144
	v_fmac_f32_e32 v145, v143, v142
	v_fma_f32 v141, -v141, v145, v144
	v_div_fmas_f32 v141, v141, v142, v145
	v_div_fixup_f32 v134, v135, v134, v129
	v_div_fixup_f32 v140, v141, v140, v113
	v_bfe_u32 v135, v134, 16, 1
	v_bfe_u32 v141, v140, 16, 1
	v_add3_u32 v134, v134, v135, s1
	v_add3_u32 v140, v140, v141, s1
	ds_write_b16_d16_hi v147, v134 offset:7344
	ds_write_b16_d16_hi v147, v140 offset:7472
	v_mul_f32_e32 v134, 0xbfb8aa3b, v82
	v_mul_f32_e32 v140, 0xbfb8aa3b, v66
	v_exp_f32_e32 v134, v134
	v_exp_f32_e32 v140, v140
	v_add_f32_e32 v134, 1.0, v134
	v_add_f32_e32 v140, 1.0, v140
	v_div_scale_f32 v135, s[2:3], v134, v134, v82
	v_div_scale_f32 v141, s[2:3], v140, v140, v66
	v_rcp_f32_e32 v136, v135
	v_rcp_f32_e32 v142, v141
	v_fma_f32 v137, -v135, v136, 1.0
	v_fma_f32 v143, -v141, v142, 1.0
	v_fmac_f32_e32 v136, v137, v136
	v_fmac_f32_e32 v142, v143, v142
	v_div_scale_f32 v138, vcc, v82, v134, v82
	v_mul_f32_e32 v139, v138, v136
	v_fma_f32 v137, -v135, v139, v138
	v_fmac_f32_e32 v139, v137, v136
	v_fma_f32 v135, -v135, v139, v138
	v_div_fmas_f32 v135, v135, v136, v139
	v_div_scale_f32 v144, vcc, v66, v140, v66
	v_mul_f32_e32 v145, v144, v142
	v_fma_f32 v143, -v141, v145, v144
	v_fmac_f32_e32 v145, v143, v142
	v_fma_f32 v141, -v141, v145, v144
	v_div_fmas_f32 v141, v141, v142, v145
	v_div_fixup_f32 v134, v135, v134, v82
	v_div_fixup_f32 v140, v141, v140, v66
	v_bfe_u32 v135, v134, 16, 1
	v_bfe_u32 v141, v140, 16, 1
	v_add3_u32 v134, v134, v135, s1
	v_add3_u32 v140, v140, v141, s1
	ds_write_b16_d16_hi v147, v134 offset:64
	ds_write_b16_d16_hi v147, v140 offset:192
	v_mul_f32_e32 v134, 0xbfb8aa3b, v83
	v_mul_f32_e32 v140, 0xbfb8aa3b, v67
	v_exp_f32_e32 v134, v134
	v_exp_f32_e32 v140, v140
	v_add_f32_e32 v134, 1.0, v134
	v_add_f32_e32 v140, 1.0, v140
	v_div_scale_f32 v135, s[2:3], v134, v134, v83
	v_div_scale_f32 v141, s[2:3], v140, v140, v67
	v_rcp_f32_e32 v136, v135
	v_rcp_f32_e32 v142, v141
	v_fma_f32 v137, -v135, v136, 1.0
	v_fma_f32 v143, -v141, v142, 1.0
	v_fmac_f32_e32 v136, v137, v136
	v_fmac_f32_e32 v142, v143, v142
	v_div_scale_f32 v138, vcc, v83, v134, v83
	v_mul_f32_e32 v139, v138, v136
	v_fma_f32 v137, -v135, v139, v138
	v_fmac_f32_e32 v139, v137, v136
	v_fma_f32 v135, -v135, v139, v138
	v_div_fmas_f32 v135, v135, v136, v139
	v_div_scale_f32 v144, vcc, v67, v140, v67
	v_mul_f32_e32 v145, v144, v142
	v_fma_f32 v143, -v141, v145, v144
	v_fmac_f32_e32 v145, v143, v142
	v_fma_f32 v141, -v141, v145, v144
	v_div_fmas_f32 v141, v141, v142, v145
	v_div_fixup_f32 v134, v135, v134, v83
	v_div_fixup_f32 v140, v141, v140, v67
	v_bfe_u32 v135, v134, 16, 1
	v_bfe_u32 v141, v140, 16, 1
	v_add3_u32 v134, v134, v135, s1
	v_add3_u32 v140, v140, v141, s1
	ds_write_b16_d16_hi v147, v134 offset:336
	ds_write_b16_d16_hi v147, v140 offset:464
	v_mul_f32_e32 v134, 0xbfb8aa3b, v84
	v_mul_f32_e32 v140, 0xbfb8aa3b, v68
	v_exp_f32_e32 v134, v134
	v_exp_f32_e32 v140, v140
	v_add_f32_e32 v134, 1.0, v134
	v_add_f32_e32 v140, 1.0, v140
	v_div_scale_f32 v135, s[2:3], v134, v134, v84
	v_div_scale_f32 v141, s[2:3], v140, v140, v68
	v_rcp_f32_e32 v136, v135
	v_rcp_f32_e32 v142, v141
	v_fma_f32 v137, -v135, v136, 1.0
	v_fma_f32 v143, -v141, v142, 1.0
	v_fmac_f32_e32 v136, v137, v136
	v_fmac_f32_e32 v142, v143, v142
	v_div_scale_f32 v138, vcc, v84, v134, v84
	v_mul_f32_e32 v139, v138, v136
	v_fma_f32 v137, -v135, v139, v138
	v_fmac_f32_e32 v139, v137, v136
	v_fma_f32 v135, -v135, v139, v138
	v_div_fmas_f32 v135, v135, v136, v139
	v_div_scale_f32 v144, vcc, v68, v140, v68
	v_mul_f32_e32 v145, v144, v142
	v_fma_f32 v143, -v141, v145, v144
	v_fmac_f32_e32 v145, v143, v142
	v_fma_f32 v141, -v141, v145, v144
	v_div_fmas_f32 v141, v141, v142, v145
	v_div_fixup_f32 v134, v135, v134, v84
	v_div_fixup_f32 v140, v141, v140, v68
	v_bfe_u32 v135, v134, 16, 1
	v_bfe_u32 v141, v140, 16, 1
	v_add3_u32 v134, v134, v135, s1
	v_add3_u32 v140, v140, v141, s1
	ds_write_b16_d16_hi v147, v134 offset:608
	ds_write_b16_d16_hi v147, v140 offset:736
	v_mul_f32_e32 v134, 0xbfb8aa3b, v85
	v_mul_f32_e32 v140, 0xbfb8aa3b, v69
	v_exp_f32_e32 v134, v134
	v_exp_f32_e32 v140, v140
	v_add_f32_e32 v134, 1.0, v134
	v_add_f32_e32 v140, 1.0, v140
	v_div_scale_f32 v135, s[2:3], v134, v134, v85
	v_div_scale_f32 v141, s[2:3], v140, v140, v69
	v_rcp_f32_e32 v136, v135
	v_rcp_f32_e32 v142, v141
	v_fma_f32 v137, -v135, v136, 1.0
	v_fma_f32 v143, -v141, v142, 1.0
	v_fmac_f32_e32 v136, v137, v136
	v_fmac_f32_e32 v142, v143, v142
	v_div_scale_f32 v138, vcc, v85, v134, v85
	v_mul_f32_e32 v139, v138, v136
	v_fma_f32 v137, -v135, v139, v138
	v_fmac_f32_e32 v139, v137, v136
	v_fma_f32 v135, -v135, v139, v138
	v_div_fmas_f32 v135, v135, v136, v139
	v_div_scale_f32 v144, vcc, v69, v140, v69
	v_mul_f32_e32 v145, v144, v142
	v_fma_f32 v143, -v141, v145, v144
	v_fmac_f32_e32 v145, v143, v142
	v_fma_f32 v141, -v141, v145, v144
	v_div_fmas_f32 v141, v141, v142, v145
	v_div_fixup_f32 v134, v135, v134, v85
	v_div_fixup_f32 v140, v141, v140, v69
	v_bfe_u32 v135, v134, 16, 1
	v_bfe_u32 v141, v140, 16, 1
	v_add3_u32 v134, v134, v135, s1
	v_add3_u32 v140, v140, v141, s1
	ds_write_b16_d16_hi v147, v134 offset:880
	ds_write_b16_d16_hi v147, v140 offset:1008
	v_mul_f32_e32 v134, 0xbfb8aa3b, v86
	v_mul_f32_e32 v140, 0xbfb8aa3b, v70
	v_exp_f32_e32 v134, v134
	v_exp_f32_e32 v140, v140
	v_add_f32_e32 v134, 1.0, v134
	v_add_f32_e32 v140, 1.0, v140
	v_div_scale_f32 v135, s[2:3], v134, v134, v86
	v_div_scale_f32 v141, s[2:3], v140, v140, v70
	v_rcp_f32_e32 v136, v135
	v_rcp_f32_e32 v142, v141
	v_fma_f32 v137, -v135, v136, 1.0
	v_fma_f32 v143, -v141, v142, 1.0
	v_fmac_f32_e32 v136, v137, v136
	v_fmac_f32_e32 v142, v143, v142
	v_div_scale_f32 v138, vcc, v86, v134, v86
	v_mul_f32_e32 v139, v138, v136
	v_fma_f32 v137, -v135, v139, v138
	v_fmac_f32_e32 v139, v137, v136
	v_fma_f32 v135, -v135, v139, v138
	v_div_fmas_f32 v135, v135, v136, v139
	v_div_scale_f32 v144, vcc, v70, v140, v70
	v_mul_f32_e32 v145, v144, v142
	v_fma_f32 v143, -v141, v145, v144
	v_fmac_f32_e32 v145, v143, v142
	v_fma_f32 v141, -v141, v145, v144
	v_div_fmas_f32 v141, v141, v142, v145
	v_div_fixup_f32 v134, v135, v134, v86
	v_div_fixup_f32 v140, v141, v140, v70
	v_bfe_u32 v135, v134, 16, 1
	v_bfe_u32 v141, v140, 16, 1
	v_add3_u32 v134, v134, v135, s1
	v_add3_u32 v140, v140, v141, s1
	ds_write_b16_d16_hi v147, v134 offset:2240
	ds_write_b16_d16_hi v147, v140 offset:2368
	v_mul_f32_e32 v134, 0xbfb8aa3b, v87
	v_mul_f32_e32 v140, 0xbfb8aa3b, v71
	v_exp_f32_e32 v134, v134
	v_exp_f32_e32 v140, v140
	v_add_f32_e32 v134, 1.0, v134
	v_add_f32_e32 v140, 1.0, v140
	v_div_scale_f32 v135, s[2:3], v134, v134, v87
	v_div_scale_f32 v141, s[2:3], v140, v140, v71
	v_rcp_f32_e32 v136, v135
	v_rcp_f32_e32 v142, v141
	v_fma_f32 v137, -v135, v136, 1.0
	v_fma_f32 v143, -v141, v142, 1.0
	v_fmac_f32_e32 v136, v137, v136
	v_fmac_f32_e32 v142, v143, v142
	v_div_scale_f32 v138, vcc, v87, v134, v87
	v_mul_f32_e32 v139, v138, v136
	v_fma_f32 v137, -v135, v139, v138
	v_fmac_f32_e32 v139, v137, v136
	v_fma_f32 v135, -v135, v139, v138
	v_div_fmas_f32 v135, v135, v136, v139
	v_div_scale_f32 v144, vcc, v71, v140, v71
	v_mul_f32_e32 v145, v144, v142
	v_fma_f32 v143, -v141, v145, v144
	v_fmac_f32_e32 v145, v143, v142
	v_fma_f32 v141, -v141, v145, v144
	v_div_fmas_f32 v141, v141, v142, v145
	v_div_fixup_f32 v134, v135, v134, v87
	v_div_fixup_f32 v140, v141, v140, v71
	v_bfe_u32 v135, v134, 16, 1
	v_bfe_u32 v141, v140, 16, 1
	v_add3_u32 v134, v134, v135, s1
	v_add3_u32 v140, v140, v141, s1
	ds_write_b16_d16_hi v147, v134 offset:2512
	ds_write_b16_d16_hi v147, v140 offset:2640
	v_mul_f32_e32 v134, 0xbfb8aa3b, v88
	v_mul_f32_e32 v140, 0xbfb8aa3b, v72
	v_exp_f32_e32 v134, v134
	v_exp_f32_e32 v140, v140
	v_add_f32_e32 v134, 1.0, v134
	v_add_f32_e32 v140, 1.0, v140
	v_div_scale_f32 v135, s[2:3], v134, v134, v88
	v_div_scale_f32 v141, s[2:3], v140, v140, v72
	v_rcp_f32_e32 v136, v135
	v_rcp_f32_e32 v142, v141
	v_fma_f32 v137, -v135, v136, 1.0
	v_fma_f32 v143, -v141, v142, 1.0
	v_fmac_f32_e32 v136, v137, v136
	v_fmac_f32_e32 v142, v143, v142
	v_div_scale_f32 v138, vcc, v88, v134, v88
	v_mul_f32_e32 v139, v138, v136
	v_fma_f32 v137, -v135, v139, v138
	v_fmac_f32_e32 v139, v137, v136
	v_fma_f32 v135, -v135, v139, v138
	v_div_fmas_f32 v135, v135, v136, v139
	v_div_scale_f32 v144, vcc, v72, v140, v72
	v_mul_f32_e32 v145, v144, v142
	v_fma_f32 v143, -v141, v145, v144
	v_fmac_f32_e32 v145, v143, v142
	v_fma_f32 v141, -v141, v145, v144
	v_div_fmas_f32 v141, v141, v142, v145
	v_div_fixup_f32 v134, v135, v134, v88
	v_div_fixup_f32 v140, v141, v140, v72
	v_bfe_u32 v135, v134, 16, 1
	v_bfe_u32 v141, v140, 16, 1
	v_add3_u32 v134, v134, v135, s1
	v_add3_u32 v140, v140, v141, s1
	ds_write_b16_d16_hi v147, v134 offset:2784
	ds_write_b16_d16_hi v147, v140 offset:2912
	v_mul_f32_e32 v134, 0xbfb8aa3b, v89
	v_mul_f32_e32 v140, 0xbfb8aa3b, v73
	v_exp_f32_e32 v134, v134
	v_exp_f32_e32 v140, v140
	v_add_f32_e32 v134, 1.0, v134
	v_add_f32_e32 v140, 1.0, v140
	v_div_scale_f32 v135, s[2:3], v134, v134, v89
	v_div_scale_f32 v141, s[2:3], v140, v140, v73
	v_rcp_f32_e32 v136, v135
	v_rcp_f32_e32 v142, v141
	v_fma_f32 v137, -v135, v136, 1.0
	v_fma_f32 v143, -v141, v142, 1.0
	v_fmac_f32_e32 v136, v137, v136
	v_fmac_f32_e32 v142, v143, v142
	v_div_scale_f32 v138, vcc, v89, v134, v89
	v_mul_f32_e32 v139, v138, v136
	v_fma_f32 v137, -v135, v139, v138
	v_fmac_f32_e32 v139, v137, v136
	v_fma_f32 v135, -v135, v139, v138
	v_div_fmas_f32 v135, v135, v136, v139
	v_div_scale_f32 v144, vcc, v73, v140, v73
	v_mul_f32_e32 v145, v144, v142
	v_fma_f32 v143, -v141, v145, v144
	v_fmac_f32_e32 v145, v143, v142
	v_fma_f32 v141, -v141, v145, v144
	v_div_fmas_f32 v141, v141, v142, v145
	v_div_fixup_f32 v134, v135, v134, v89
	v_div_fixup_f32 v140, v141, v140, v73
	v_bfe_u32 v135, v134, 16, 1
	v_bfe_u32 v141, v140, 16, 1
	v_add3_u32 v134, v134, v135, s1
	v_add3_u32 v140, v140, v141, s1
	ds_write_b16_d16_hi v147, v134 offset:3056
	ds_write_b16_d16_hi v147, v140 offset:3184
	v_mul_f32_e32 v134, 0xbfb8aa3b, v90
	v_mul_f32_e32 v140, 0xbfb8aa3b, v74
	v_exp_f32_e32 v134, v134
	v_exp_f32_e32 v140, v140
	v_add_f32_e32 v134, 1.0, v134
	v_add_f32_e32 v140, 1.0, v140
	v_div_scale_f32 v135, s[2:3], v134, v134, v90
	v_div_scale_f32 v141, s[2:3], v140, v140, v74
	v_rcp_f32_e32 v136, v135
	v_rcp_f32_e32 v142, v141
	v_fma_f32 v137, -v135, v136, 1.0
	v_fma_f32 v143, -v141, v142, 1.0
	v_fmac_f32_e32 v136, v137, v136
	v_fmac_f32_e32 v142, v143, v142
	v_div_scale_f32 v138, vcc, v90, v134, v90
	v_mul_f32_e32 v139, v138, v136
	v_fma_f32 v137, -v135, v139, v138
	v_fmac_f32_e32 v139, v137, v136
	v_fma_f32 v135, -v135, v139, v138
	v_div_fmas_f32 v135, v135, v136, v139
	v_div_scale_f32 v144, vcc, v74, v140, v74
	v_mul_f32_e32 v145, v144, v142
	v_fma_f32 v143, -v141, v145, v144
	v_fmac_f32_e32 v145, v143, v142
	v_fma_f32 v141, -v141, v145, v144
	v_div_fmas_f32 v141, v141, v142, v145
	v_div_fixup_f32 v134, v135, v134, v90
	v_div_fixup_f32 v140, v141, v140, v74
	v_bfe_u32 v135, v134, 16, 1
	v_bfe_u32 v141, v140, 16, 1
	v_add3_u32 v134, v134, v135, s1
	v_add3_u32 v140, v140, v141, s1
	ds_write_b16_d16_hi v147, v134 offset:4416
	ds_write_b16_d16_hi v147, v140 offset:4544
	v_mul_f32_e32 v134, 0xbfb8aa3b, v91
	v_mul_f32_e32 v140, 0xbfb8aa3b, v75
	v_exp_f32_e32 v134, v134
	v_exp_f32_e32 v140, v140
	v_add_f32_e32 v134, 1.0, v134
	v_add_f32_e32 v140, 1.0, v140
	v_div_scale_f32 v135, s[2:3], v134, v134, v91
	v_div_scale_f32 v141, s[2:3], v140, v140, v75
	v_rcp_f32_e32 v136, v135
	v_rcp_f32_e32 v142, v141
	v_fma_f32 v137, -v135, v136, 1.0
	v_fma_f32 v143, -v141, v142, 1.0
	v_fmac_f32_e32 v136, v137, v136
	v_fmac_f32_e32 v142, v143, v142
	v_div_scale_f32 v138, vcc, v91, v134, v91
	v_mul_f32_e32 v139, v138, v136
	v_fma_f32 v137, -v135, v139, v138
	v_fmac_f32_e32 v139, v137, v136
	v_fma_f32 v135, -v135, v139, v138
	v_div_fmas_f32 v135, v135, v136, v139
	v_div_scale_f32 v144, vcc, v75, v140, v75
	v_mul_f32_e32 v145, v144, v142
	v_fma_f32 v143, -v141, v145, v144
	v_fmac_f32_e32 v145, v143, v142
	v_fma_f32 v141, -v141, v145, v144
	v_div_fmas_f32 v141, v141, v142, v145
	v_div_fixup_f32 v134, v135, v134, v91
	v_div_fixup_f32 v140, v141, v140, v75
	v_bfe_u32 v135, v134, 16, 1
	v_bfe_u32 v141, v140, 16, 1
	v_add3_u32 v134, v134, v135, s1
	v_add3_u32 v140, v140, v141, s1
	ds_write_b16_d16_hi v147, v134 offset:4688
	ds_write_b16_d16_hi v147, v140 offset:4816
	v_mul_f32_e32 v134, 0xbfb8aa3b, v92
	v_mul_f32_e32 v140, 0xbfb8aa3b, v76
	v_exp_f32_e32 v134, v134
	v_exp_f32_e32 v140, v140
	v_add_f32_e32 v134, 1.0, v134
	v_add_f32_e32 v140, 1.0, v140
	v_div_scale_f32 v135, s[2:3], v134, v134, v92
	v_div_scale_f32 v141, s[2:3], v140, v140, v76
	v_rcp_f32_e32 v136, v135
	v_rcp_f32_e32 v142, v141
	v_fma_f32 v137, -v135, v136, 1.0
	v_fma_f32 v143, -v141, v142, 1.0
	v_fmac_f32_e32 v136, v137, v136
	v_fmac_f32_e32 v142, v143, v142
	v_div_scale_f32 v138, vcc, v92, v134, v92
	v_mul_f32_e32 v139, v138, v136
	v_fma_f32 v137, -v135, v139, v138
	v_fmac_f32_e32 v139, v137, v136
	v_fma_f32 v135, -v135, v139, v138
	v_div_fmas_f32 v135, v135, v136, v139
	v_div_scale_f32 v144, vcc, v76, v140, v76
	v_mul_f32_e32 v145, v144, v142
	v_fma_f32 v143, -v141, v145, v144
	v_fmac_f32_e32 v145, v143, v142
	v_fma_f32 v141, -v141, v145, v144
	v_div_fmas_f32 v141, v141, v142, v145
	v_div_fixup_f32 v134, v135, v134, v92
	v_div_fixup_f32 v140, v141, v140, v76
	v_bfe_u32 v135, v134, 16, 1
	v_bfe_u32 v141, v140, 16, 1
	v_add3_u32 v134, v134, v135, s1
	v_add3_u32 v140, v140, v141, s1
	ds_write_b16_d16_hi v147, v134 offset:4960
	ds_write_b16_d16_hi v147, v140 offset:5088
	v_mul_f32_e32 v134, 0xbfb8aa3b, v93
	v_mul_f32_e32 v140, 0xbfb8aa3b, v77
	v_exp_f32_e32 v134, v134
	v_exp_f32_e32 v140, v140
	v_add_f32_e32 v134, 1.0, v134
	v_add_f32_e32 v140, 1.0, v140
	v_div_scale_f32 v135, s[2:3], v134, v134, v93
	v_div_scale_f32 v141, s[2:3], v140, v140, v77
	v_rcp_f32_e32 v136, v135
	v_rcp_f32_e32 v142, v141
	v_fma_f32 v137, -v135, v136, 1.0
	v_fma_f32 v143, -v141, v142, 1.0
	v_fmac_f32_e32 v136, v137, v136
	v_fmac_f32_e32 v142, v143, v142
	v_div_scale_f32 v138, vcc, v93, v134, v93
	v_mul_f32_e32 v139, v138, v136
	v_fma_f32 v137, -v135, v139, v138
	v_fmac_f32_e32 v139, v137, v136
	v_fma_f32 v135, -v135, v139, v138
	v_div_fmas_f32 v135, v135, v136, v139
	v_div_scale_f32 v144, vcc, v77, v140, v77
	v_mul_f32_e32 v145, v144, v142
	v_fma_f32 v143, -v141, v145, v144
	v_fmac_f32_e32 v145, v143, v142
	v_fma_f32 v141, -v141, v145, v144
	v_div_fmas_f32 v141, v141, v142, v145
	v_div_fixup_f32 v134, v135, v134, v93
	v_div_fixup_f32 v140, v141, v140, v77
	v_bfe_u32 v135, v134, 16, 1
	v_bfe_u32 v141, v140, 16, 1
	v_add3_u32 v134, v134, v135, s1
	v_add3_u32 v140, v140, v141, s1
	ds_write_b16_d16_hi v147, v134 offset:5232
	ds_write_b16_d16_hi v147, v140 offset:5360
	v_mul_f32_e32 v134, 0xbfb8aa3b, v94
	v_mul_f32_e32 v140, 0xbfb8aa3b, v78
	v_exp_f32_e32 v134, v134
	v_exp_f32_e32 v140, v140
	v_add_f32_e32 v134, 1.0, v134
	v_add_f32_e32 v140, 1.0, v140
	v_div_scale_f32 v135, s[2:3], v134, v134, v94
	v_div_scale_f32 v141, s[2:3], v140, v140, v78
	v_rcp_f32_e32 v136, v135
	v_rcp_f32_e32 v142, v141
	v_fma_f32 v137, -v135, v136, 1.0
	v_fma_f32 v143, -v141, v142, 1.0
	v_fmac_f32_e32 v136, v137, v136
	v_fmac_f32_e32 v142, v143, v142
	v_div_scale_f32 v138, vcc, v94, v134, v94
	v_mul_f32_e32 v139, v138, v136
	v_fma_f32 v137, -v135, v139, v138
	v_fmac_f32_e32 v139, v137, v136
	v_fma_f32 v135, -v135, v139, v138
	v_div_fmas_f32 v135, v135, v136, v139
	v_div_scale_f32 v144, vcc, v78, v140, v78
	v_mul_f32_e32 v145, v144, v142
	v_fma_f32 v143, -v141, v145, v144
	v_fmac_f32_e32 v145, v143, v142
	v_fma_f32 v141, -v141, v145, v144
	v_div_fmas_f32 v141, v141, v142, v145
	v_div_fixup_f32 v134, v135, v134, v94
	v_div_fixup_f32 v140, v141, v140, v78
	v_bfe_u32 v135, v134, 16, 1
	v_bfe_u32 v141, v140, 16, 1
	v_add3_u32 v134, v134, v135, s1
	v_add3_u32 v140, v140, v141, s1
	ds_write_b16_d16_hi v147, v134 offset:6592
	ds_write_b16_d16_hi v147, v140 offset:6720
	v_mul_f32_e32 v134, 0xbfb8aa3b, v95
	v_mul_f32_e32 v140, 0xbfb8aa3b, v79
	v_exp_f32_e32 v134, v134
	v_exp_f32_e32 v140, v140
	v_add_f32_e32 v134, 1.0, v134
	v_add_f32_e32 v140, 1.0, v140
	v_div_scale_f32 v135, s[2:3], v134, v134, v95
	v_div_scale_f32 v141, s[2:3], v140, v140, v79
	v_rcp_f32_e32 v136, v135
	v_rcp_f32_e32 v142, v141
	v_fma_f32 v137, -v135, v136, 1.0
	v_fma_f32 v143, -v141, v142, 1.0
	v_fmac_f32_e32 v136, v137, v136
	v_fmac_f32_e32 v142, v143, v142
	v_div_scale_f32 v138, vcc, v95, v134, v95
	v_mul_f32_e32 v139, v138, v136
	v_fma_f32 v137, -v135, v139, v138
	v_fmac_f32_e32 v139, v137, v136
	v_fma_f32 v135, -v135, v139, v138
	v_div_fmas_f32 v135, v135, v136, v139
	v_div_scale_f32 v144, vcc, v79, v140, v79
	v_mul_f32_e32 v145, v144, v142
	v_fma_f32 v143, -v141, v145, v144
	v_fmac_f32_e32 v145, v143, v142
	v_fma_f32 v141, -v141, v145, v144
	v_div_fmas_f32 v141, v141, v142, v145
	v_div_fixup_f32 v134, v135, v134, v95
	v_div_fixup_f32 v140, v141, v140, v79
	v_bfe_u32 v135, v134, 16, 1
	v_bfe_u32 v141, v140, 16, 1
	v_add3_u32 v134, v134, v135, s1
	v_add3_u32 v140, v140, v141, s1
	ds_write_b16_d16_hi v147, v134 offset:6864
	ds_write_b16_d16_hi v147, v140 offset:6992
	v_mul_f32_e32 v134, 0xbfb8aa3b, v96
	v_mul_f32_e32 v140, 0xbfb8aa3b, v80
	v_exp_f32_e32 v134, v134
	v_exp_f32_e32 v140, v140
	v_add_f32_e32 v134, 1.0, v134
	v_add_f32_e32 v140, 1.0, v140
	v_div_scale_f32 v135, s[2:3], v134, v134, v96
	v_div_scale_f32 v141, s[2:3], v140, v140, v80
	v_rcp_f32_e32 v136, v135
	v_rcp_f32_e32 v142, v141
	v_fma_f32 v137, -v135, v136, 1.0
	v_fma_f32 v143, -v141, v142, 1.0
	v_fmac_f32_e32 v136, v137, v136
	v_fmac_f32_e32 v142, v143, v142
	v_div_scale_f32 v138, vcc, v96, v134, v96
	v_mul_f32_e32 v139, v138, v136
	v_fma_f32 v137, -v135, v139, v138
	v_fmac_f32_e32 v139, v137, v136
	v_fma_f32 v135, -v135, v139, v138
	v_div_fmas_f32 v135, v135, v136, v139
	v_div_scale_f32 v144, vcc, v80, v140, v80
	v_mul_f32_e32 v145, v144, v142
	v_fma_f32 v143, -v141, v145, v144
	v_fmac_f32_e32 v145, v143, v142
	v_fma_f32 v141, -v141, v145, v144
	v_div_fmas_f32 v141, v141, v142, v145
	v_div_fixup_f32 v134, v135, v134, v96
	v_div_fixup_f32 v140, v141, v140, v80
	v_bfe_u32 v135, v134, 16, 1
	v_bfe_u32 v141, v140, 16, 1
	v_add3_u32 v134, v134, v135, s1
	v_add3_u32 v140, v140, v141, s1
	ds_write_b16_d16_hi v147, v134 offset:7136
	ds_write_b16_d16_hi v147, v140 offset:7264
	v_mul_f32_e32 v134, 0xbfb8aa3b, v97
	v_mul_f32_e32 v140, 0xbfb8aa3b, v81
	v_exp_f32_e32 v134, v134
	v_exp_f32_e32 v140, v140
	v_add_f32_e32 v134, 1.0, v134
	v_add_f32_e32 v140, 1.0, v140
	v_div_scale_f32 v135, s[2:3], v134, v134, v97
	v_div_scale_f32 v141, s[2:3], v140, v140, v81
	v_rcp_f32_e32 v136, v135
	v_rcp_f32_e32 v142, v141
	v_fma_f32 v137, -v135, v136, 1.0
	v_fma_f32 v143, -v141, v142, 1.0
	v_fmac_f32_e32 v136, v137, v136
	v_fmac_f32_e32 v142, v143, v142
	v_div_scale_f32 v138, vcc, v97, v134, v97
	v_mul_f32_e32 v139, v138, v136
	v_fma_f32 v137, -v135, v139, v138
	v_fmac_f32_e32 v139, v137, v136
	v_fma_f32 v135, -v135, v139, v138
	v_div_fmas_f32 v135, v135, v136, v139
	v_div_scale_f32 v144, vcc, v81, v140, v81
	v_mul_f32_e32 v145, v144, v142
	v_fma_f32 v143, -v141, v145, v144
	v_fmac_f32_e32 v145, v143, v142
	v_fma_f32 v141, -v141, v145, v144
	v_div_fmas_f32 v141, v141, v142, v145
	v_div_fixup_f32 v134, v135, v134, v97
	v_div_fixup_f32 v140, v141, v140, v81
	v_bfe_u32 v135, v134, 16, 1
	v_bfe_u32 v141, v140, 16, 1
	v_add3_u32 v134, v134, v135, s1
	v_add3_u32 v140, v140, v141, s1
	ds_write_b16_d16_hi v147, v134 offset:7408
	ds_write_b16_d16_hi v147, v140 offset:7536
	s_waitcnt lgkmcnt(0)
	ds_read_b128 v[164:167], v148 offset:0
	ds_read_b128 v[168:171], v148 offset:1088
	ds_read_b128 v[172:175], v148 offset:2176
	ds_read_b128 v[224:227], v148 offset:3264
	ds_read_b128 v[228:231], v148 offset:4352
	ds_read_b128 v[232:235], v148 offset:5440
	ds_read_b128 v[236:239], v148 offset:6528
	ds_read_b128 v[240:243], v148 offset:7616
	s_waitcnt lgkmcnt(7)
	global_store_dwordx4 v[158:159], v[164:167], off
	v_lshl_add_u64 v[158:159], v[158:159], 0, s[100:101]
	s_waitcnt lgkmcnt(6)
	global_store_dwordx4 v[158:159], v[168:171], off
	v_lshl_add_u64 v[158:159], v[158:159], 0, s[100:101]
	s_waitcnt lgkmcnt(5)
	global_store_dwordx4 v[158:159], v[172:175], off
	v_lshl_add_u64 v[158:159], v[158:159], 0, s[100:101]
	s_waitcnt lgkmcnt(4)
	global_store_dwordx4 v[158:159], v[224:227], off
	v_lshl_add_u64 v[158:159], v[158:159], 0, s[100:101]
	s_waitcnt lgkmcnt(3)
	global_store_dwordx4 v[158:159], v[228:231], off
	v_lshl_add_u64 v[158:159], v[158:159], 0, s[100:101]
	s_waitcnt lgkmcnt(2)
	global_store_dwordx4 v[158:159], v[232:235], off
	v_lshl_add_u64 v[158:159], v[158:159], 0, s[100:101]
	s_waitcnt lgkmcnt(1)
	global_store_dwordx4 v[158:159], v[236:239], off
	v_lshl_add_u64 v[158:159], v[158:159], 0, s[100:101]
	s_waitcnt lgkmcnt(0)
	global_store_dwordx4 v[158:159], v[240:243], off
	v_lshl_add_u64 v[158:159], v[158:159], 0, s[100:101]
	v_mul_f32_e32 v134, 0xbfb8aa3b, v50
	v_mul_f32_e32 v140, 0xbfb8aa3b, v34
	v_exp_f32_e32 v134, v134
	v_exp_f32_e32 v140, v140
	v_add_f32_e32 v134, 1.0, v134
	v_add_f32_e32 v140, 1.0, v140
	v_div_scale_f32 v135, s[2:3], v134, v134, v50
	v_div_scale_f32 v141, s[2:3], v140, v140, v34
	v_rcp_f32_e32 v136, v135
	v_rcp_f32_e32 v142, v141
	v_fma_f32 v137, -v135, v136, 1.0
	v_fma_f32 v143, -v141, v142, 1.0
	v_fmac_f32_e32 v136, v137, v136
	v_fmac_f32_e32 v142, v143, v142
	v_div_scale_f32 v138, vcc, v50, v134, v50
	v_mul_f32_e32 v139, v138, v136
	v_fma_f32 v137, -v135, v139, v138
	v_fmac_f32_e32 v139, v137, v136
	v_fma_f32 v135, -v135, v139, v138
	v_div_fmas_f32 v135, v135, v136, v139
	v_div_scale_f32 v144, vcc, v34, v140, v34
	v_mul_f32_e32 v145, v144, v142
	v_fma_f32 v143, -v141, v145, v144
	v_fmac_f32_e32 v145, v143, v142
	v_fma_f32 v141, -v141, v145, v144
	v_div_fmas_f32 v141, v141, v142, v145
	v_div_fixup_f32 v134, v135, v134, v50
	v_div_fixup_f32 v140, v141, v140, v34
	v_bfe_u32 v135, v134, 16, 1
	v_bfe_u32 v141, v140, 16, 1
	v_add3_u32 v134, v134, v135, s1
	v_add3_u32 v140, v140, v141, s1
	ds_write_b16_d16_hi v147, v134 offset:0
	ds_write_b16_d16_hi v147, v140 offset:128
	v_mul_f32_e32 v134, 0xbfb8aa3b, v51
	v_mul_f32_e32 v140, 0xbfb8aa3b, v35
	v_exp_f32_e32 v134, v134
	v_exp_f32_e32 v140, v140
	v_add_f32_e32 v134, 1.0, v134
	v_add_f32_e32 v140, 1.0, v140
	v_div_scale_f32 v135, s[2:3], v134, v134, v51
	v_div_scale_f32 v141, s[2:3], v140, v140, v35
	v_rcp_f32_e32 v136, v135
	v_rcp_f32_e32 v142, v141
	v_fma_f32 v137, -v135, v136, 1.0
	v_fma_f32 v143, -v141, v142, 1.0
	v_fmac_f32_e32 v136, v137, v136
	v_fmac_f32_e32 v142, v143, v142
	v_div_scale_f32 v138, vcc, v51, v134, v51
	v_mul_f32_e32 v139, v138, v136
	v_fma_f32 v137, -v135, v139, v138
	v_fmac_f32_e32 v139, v137, v136
	v_fma_f32 v135, -v135, v139, v138
	v_div_fmas_f32 v135, v135, v136, v139
	v_div_scale_f32 v144, vcc, v35, v140, v35
	v_mul_f32_e32 v145, v144, v142
	v_fma_f32 v143, -v141, v145, v144
	v_fmac_f32_e32 v145, v143, v142
	v_fma_f32 v141, -v141, v145, v144
	v_div_fmas_f32 v141, v141, v142, v145
	v_div_fixup_f32 v134, v135, v134, v51
	v_div_fixup_f32 v140, v141, v140, v35
	v_bfe_u32 v135, v134, 16, 1
	v_bfe_u32 v141, v140, 16, 1
	v_add3_u32 v134, v134, v135, s1
	v_add3_u32 v140, v140, v141, s1
	ds_write_b16_d16_hi v147, v134 offset:272
	ds_write_b16_d16_hi v147, v140 offset:400
	v_mul_f32_e32 v134, 0xbfb8aa3b, v52
	v_mul_f32_e32 v140, 0xbfb8aa3b, v36
	v_exp_f32_e32 v134, v134
	v_exp_f32_e32 v140, v140
	v_add_f32_e32 v134, 1.0, v134
	v_add_f32_e32 v140, 1.0, v140
	v_div_scale_f32 v135, s[2:3], v134, v134, v52
	v_div_scale_f32 v141, s[2:3], v140, v140, v36
	v_rcp_f32_e32 v136, v135
	v_rcp_f32_e32 v142, v141
	v_fma_f32 v137, -v135, v136, 1.0
	v_fma_f32 v143, -v141, v142, 1.0
	v_fmac_f32_e32 v136, v137, v136
	v_fmac_f32_e32 v142, v143, v142
	v_div_scale_f32 v138, vcc, v52, v134, v52
	v_mul_f32_e32 v139, v138, v136
	v_fma_f32 v137, -v135, v139, v138
	v_fmac_f32_e32 v139, v137, v136
	v_fma_f32 v135, -v135, v139, v138
	v_div_fmas_f32 v135, v135, v136, v139
	v_div_scale_f32 v144, vcc, v36, v140, v36
	v_mul_f32_e32 v145, v144, v142
	v_fma_f32 v143, -v141, v145, v144
	v_fmac_f32_e32 v145, v143, v142
	v_fma_f32 v141, -v141, v145, v144
	v_div_fmas_f32 v141, v141, v142, v145
	v_div_fixup_f32 v134, v135, v134, v52
	v_div_fixup_f32 v140, v141, v140, v36
	v_bfe_u32 v135, v134, 16, 1
	v_bfe_u32 v141, v140, 16, 1
	v_add3_u32 v134, v134, v135, s1
	v_add3_u32 v140, v140, v141, s1
	ds_write_b16_d16_hi v147, v134 offset:544
	ds_write_b16_d16_hi v147, v140 offset:672
	v_mul_f32_e32 v134, 0xbfb8aa3b, v53
	v_mul_f32_e32 v140, 0xbfb8aa3b, v37
	v_exp_f32_e32 v134, v134
	v_exp_f32_e32 v140, v140
	v_add_f32_e32 v134, 1.0, v134
	v_add_f32_e32 v140, 1.0, v140
	v_div_scale_f32 v135, s[2:3], v134, v134, v53
	v_div_scale_f32 v141, s[2:3], v140, v140, v37
	v_rcp_f32_e32 v136, v135
	v_rcp_f32_e32 v142, v141
	v_fma_f32 v137, -v135, v136, 1.0
	v_fma_f32 v143, -v141, v142, 1.0
	v_fmac_f32_e32 v136, v137, v136
	v_fmac_f32_e32 v142, v143, v142
	v_div_scale_f32 v138, vcc, v53, v134, v53
	v_mul_f32_e32 v139, v138, v136
	v_fma_f32 v137, -v135, v139, v138
	v_fmac_f32_e32 v139, v137, v136
	v_fma_f32 v135, -v135, v139, v138
	v_div_fmas_f32 v135, v135, v136, v139
	v_div_scale_f32 v144, vcc, v37, v140, v37
	v_mul_f32_e32 v145, v144, v142
	v_fma_f32 v143, -v141, v145, v144
	v_fmac_f32_e32 v145, v143, v142
	v_fma_f32 v141, -v141, v145, v144
	v_div_fmas_f32 v141, v141, v142, v145
	v_div_fixup_f32 v134, v135, v134, v53
	v_div_fixup_f32 v140, v141, v140, v37
	v_bfe_u32 v135, v134, 16, 1
	v_bfe_u32 v141, v140, 16, 1
	v_add3_u32 v134, v134, v135, s1
	v_add3_u32 v140, v140, v141, s1
	ds_write_b16_d16_hi v147, v134 offset:816
	ds_write_b16_d16_hi v147, v140 offset:944
	v_mul_f32_e32 v134, 0xbfb8aa3b, v54
	v_mul_f32_e32 v140, 0xbfb8aa3b, v38
	v_exp_f32_e32 v134, v134
	v_exp_f32_e32 v140, v140
	v_add_f32_e32 v134, 1.0, v134
	v_add_f32_e32 v140, 1.0, v140
	v_div_scale_f32 v135, s[2:3], v134, v134, v54
	v_div_scale_f32 v141, s[2:3], v140, v140, v38
	v_rcp_f32_e32 v136, v135
	v_rcp_f32_e32 v142, v141
	v_fma_f32 v137, -v135, v136, 1.0
	v_fma_f32 v143, -v141, v142, 1.0
	v_fmac_f32_e32 v136, v137, v136
	v_fmac_f32_e32 v142, v143, v142
	v_div_scale_f32 v138, vcc, v54, v134, v54
	v_mul_f32_e32 v139, v138, v136
	v_fma_f32 v137, -v135, v139, v138
	v_fmac_f32_e32 v139, v137, v136
	v_fma_f32 v135, -v135, v139, v138
	v_div_fmas_f32 v135, v135, v136, v139
	v_div_scale_f32 v144, vcc, v38, v140, v38
	v_mul_f32_e32 v145, v144, v142
	v_fma_f32 v143, -v141, v145, v144
	v_fmac_f32_e32 v145, v143, v142
	v_fma_f32 v141, -v141, v145, v144
	v_div_fmas_f32 v141, v141, v142, v145
	v_div_fixup_f32 v134, v135, v134, v54
	v_div_fixup_f32 v140, v141, v140, v38
	v_bfe_u32 v135, v134, 16, 1
	v_bfe_u32 v141, v140, 16, 1
	v_add3_u32 v134, v134, v135, s1
	v_add3_u32 v140, v140, v141, s1
	ds_write_b16_d16_hi v147, v134 offset:2176
	ds_write_b16_d16_hi v147, v140 offset:2304
	v_mul_f32_e32 v134, 0xbfb8aa3b, v55
	v_mul_f32_e32 v140, 0xbfb8aa3b, v39
	v_exp_f32_e32 v134, v134
	v_exp_f32_e32 v140, v140
	v_add_f32_e32 v134, 1.0, v134
	v_add_f32_e32 v140, 1.0, v140
	v_div_scale_f32 v135, s[2:3], v134, v134, v55
	v_div_scale_f32 v141, s[2:3], v140, v140, v39
	v_rcp_f32_e32 v136, v135
	v_rcp_f32_e32 v142, v141
	v_fma_f32 v137, -v135, v136, 1.0
	v_fma_f32 v143, -v141, v142, 1.0
	v_fmac_f32_e32 v136, v137, v136
	v_fmac_f32_e32 v142, v143, v142
	v_div_scale_f32 v138, vcc, v55, v134, v55
	v_mul_f32_e32 v139, v138, v136
	v_fma_f32 v137, -v135, v139, v138
	v_fmac_f32_e32 v139, v137, v136
	v_fma_f32 v135, -v135, v139, v138
	v_div_fmas_f32 v135, v135, v136, v139
	v_div_scale_f32 v144, vcc, v39, v140, v39
	v_mul_f32_e32 v145, v144, v142
	v_fma_f32 v143, -v141, v145, v144
	v_fmac_f32_e32 v145, v143, v142
	v_fma_f32 v141, -v141, v145, v144
	v_div_fmas_f32 v141, v141, v142, v145
	v_div_fixup_f32 v134, v135, v134, v55
	v_div_fixup_f32 v140, v141, v140, v39
	v_bfe_u32 v135, v134, 16, 1
	v_bfe_u32 v141, v140, 16, 1
	v_add3_u32 v134, v134, v135, s1
	v_add3_u32 v140, v140, v141, s1
	ds_write_b16_d16_hi v147, v134 offset:2448
	ds_write_b16_d16_hi v147, v140 offset:2576
	v_mul_f32_e32 v134, 0xbfb8aa3b, v56
	v_mul_f32_e32 v140, 0xbfb8aa3b, v40
	v_exp_f32_e32 v134, v134
	v_exp_f32_e32 v140, v140
	v_add_f32_e32 v134, 1.0, v134
	v_add_f32_e32 v140, 1.0, v140
	v_div_scale_f32 v135, s[2:3], v134, v134, v56
	v_div_scale_f32 v141, s[2:3], v140, v140, v40
	v_rcp_f32_e32 v136, v135
	v_rcp_f32_e32 v142, v141
	v_fma_f32 v137, -v135, v136, 1.0
	v_fma_f32 v143, -v141, v142, 1.0
	v_fmac_f32_e32 v136, v137, v136
	v_fmac_f32_e32 v142, v143, v142
	v_div_scale_f32 v138, vcc, v56, v134, v56
	v_mul_f32_e32 v139, v138, v136
	v_fma_f32 v137, -v135, v139, v138
	v_fmac_f32_e32 v139, v137, v136
	v_fma_f32 v135, -v135, v139, v138
	v_div_fmas_f32 v135, v135, v136, v139
	v_div_scale_f32 v144, vcc, v40, v140, v40
	v_mul_f32_e32 v145, v144, v142
	v_fma_f32 v143, -v141, v145, v144
	v_fmac_f32_e32 v145, v143, v142
	v_fma_f32 v141, -v141, v145, v144
	v_div_fmas_f32 v141, v141, v142, v145
	v_div_fixup_f32 v134, v135, v134, v56
	v_div_fixup_f32 v140, v141, v140, v40
	v_bfe_u32 v135, v134, 16, 1
	v_bfe_u32 v141, v140, 16, 1
	v_add3_u32 v134, v134, v135, s1
	v_add3_u32 v140, v140, v141, s1
	ds_write_b16_d16_hi v147, v134 offset:2720
	ds_write_b16_d16_hi v147, v140 offset:2848
	v_mul_f32_e32 v134, 0xbfb8aa3b, v57
	v_mul_f32_e32 v140, 0xbfb8aa3b, v41
	v_exp_f32_e32 v134, v134
	v_exp_f32_e32 v140, v140
	v_add_f32_e32 v134, 1.0, v134
	v_add_f32_e32 v140, 1.0, v140
	v_div_scale_f32 v135, s[2:3], v134, v134, v57
	v_div_scale_f32 v141, s[2:3], v140, v140, v41
	v_rcp_f32_e32 v136, v135
	v_rcp_f32_e32 v142, v141
	v_fma_f32 v137, -v135, v136, 1.0
	v_fma_f32 v143, -v141, v142, 1.0
	v_fmac_f32_e32 v136, v137, v136
	v_fmac_f32_e32 v142, v143, v142
	v_div_scale_f32 v138, vcc, v57, v134, v57
	v_mul_f32_e32 v139, v138, v136
	v_fma_f32 v137, -v135, v139, v138
	v_fmac_f32_e32 v139, v137, v136
	v_fma_f32 v135, -v135, v139, v138
	v_div_fmas_f32 v135, v135, v136, v139
	v_div_scale_f32 v144, vcc, v41, v140, v41
	v_mul_f32_e32 v145, v144, v142
	v_fma_f32 v143, -v141, v145, v144
	v_fmac_f32_e32 v145, v143, v142
	v_fma_f32 v141, -v141, v145, v144
	v_div_fmas_f32 v141, v141, v142, v145
	v_div_fixup_f32 v134, v135, v134, v57
	v_div_fixup_f32 v140, v141, v140, v41
	v_bfe_u32 v135, v134, 16, 1
	v_bfe_u32 v141, v140, 16, 1
	v_add3_u32 v134, v134, v135, s1
	v_add3_u32 v140, v140, v141, s1
	ds_write_b16_d16_hi v147, v134 offset:2992
	ds_write_b16_d16_hi v147, v140 offset:3120
	v_mul_f32_e32 v134, 0xbfb8aa3b, v58
	v_mul_f32_e32 v140, 0xbfb8aa3b, v42
	v_exp_f32_e32 v134, v134
	v_exp_f32_e32 v140, v140
	v_add_f32_e32 v134, 1.0, v134
	v_add_f32_e32 v140, 1.0, v140
	v_div_scale_f32 v135, s[2:3], v134, v134, v58
	v_div_scale_f32 v141, s[2:3], v140, v140, v42
	v_rcp_f32_e32 v136, v135
	v_rcp_f32_e32 v142, v141
	v_fma_f32 v137, -v135, v136, 1.0
	v_fma_f32 v143, -v141, v142, 1.0
	v_fmac_f32_e32 v136, v137, v136
	v_fmac_f32_e32 v142, v143, v142
	v_div_scale_f32 v138, vcc, v58, v134, v58
	v_mul_f32_e32 v139, v138, v136
	v_fma_f32 v137, -v135, v139, v138
	v_fmac_f32_e32 v139, v137, v136
	v_fma_f32 v135, -v135, v139, v138
	v_div_fmas_f32 v135, v135, v136, v139
	v_div_scale_f32 v144, vcc, v42, v140, v42
	v_mul_f32_e32 v145, v144, v142
	v_fma_f32 v143, -v141, v145, v144
	v_fmac_f32_e32 v145, v143, v142
	v_fma_f32 v141, -v141, v145, v144
	v_div_fmas_f32 v141, v141, v142, v145
	v_div_fixup_f32 v134, v135, v134, v58
	v_div_fixup_f32 v140, v141, v140, v42
	v_bfe_u32 v135, v134, 16, 1
	v_bfe_u32 v141, v140, 16, 1
	v_add3_u32 v134, v134, v135, s1
	v_add3_u32 v140, v140, v141, s1
	ds_write_b16_d16_hi v147, v134 offset:4352
	ds_write_b16_d16_hi v147, v140 offset:4480
	v_mul_f32_e32 v134, 0xbfb8aa3b, v59
	v_mul_f32_e32 v140, 0xbfb8aa3b, v43
	v_exp_f32_e32 v134, v134
	v_exp_f32_e32 v140, v140
	v_add_f32_e32 v134, 1.0, v134
	v_add_f32_e32 v140, 1.0, v140
	v_div_scale_f32 v135, s[2:3], v134, v134, v59
	v_div_scale_f32 v141, s[2:3], v140, v140, v43
	v_rcp_f32_e32 v136, v135
	v_rcp_f32_e32 v142, v141
	v_fma_f32 v137, -v135, v136, 1.0
	v_fma_f32 v143, -v141, v142, 1.0
	v_fmac_f32_e32 v136, v137, v136
	v_fmac_f32_e32 v142, v143, v142
	v_div_scale_f32 v138, vcc, v59, v134, v59
	v_mul_f32_e32 v139, v138, v136
	v_fma_f32 v137, -v135, v139, v138
	v_fmac_f32_e32 v139, v137, v136
	v_fma_f32 v135, -v135, v139, v138
	v_div_fmas_f32 v135, v135, v136, v139
	v_div_scale_f32 v144, vcc, v43, v140, v43
	v_mul_f32_e32 v145, v144, v142
	v_fma_f32 v143, -v141, v145, v144
	v_fmac_f32_e32 v145, v143, v142
	v_fma_f32 v141, -v141, v145, v144
	v_div_fmas_f32 v141, v141, v142, v145
	v_div_fixup_f32 v134, v135, v134, v59
	v_div_fixup_f32 v140, v141, v140, v43
	v_bfe_u32 v135, v134, 16, 1
	v_bfe_u32 v141, v140, 16, 1
	v_add3_u32 v134, v134, v135, s1
	v_add3_u32 v140, v140, v141, s1
	ds_write_b16_d16_hi v147, v134 offset:4624
	ds_write_b16_d16_hi v147, v140 offset:4752
	v_mul_f32_e32 v134, 0xbfb8aa3b, v60
	v_mul_f32_e32 v140, 0xbfb8aa3b, v44
	v_exp_f32_e32 v134, v134
	v_exp_f32_e32 v140, v140
	v_add_f32_e32 v134, 1.0, v134
	v_add_f32_e32 v140, 1.0, v140
	v_div_scale_f32 v135, s[2:3], v134, v134, v60
	v_div_scale_f32 v141, s[2:3], v140, v140, v44
	v_rcp_f32_e32 v136, v135
	v_rcp_f32_e32 v142, v141
	v_fma_f32 v137, -v135, v136, 1.0
	v_fma_f32 v143, -v141, v142, 1.0
	v_fmac_f32_e32 v136, v137, v136
	v_fmac_f32_e32 v142, v143, v142
	v_div_scale_f32 v138, vcc, v60, v134, v60
	v_mul_f32_e32 v139, v138, v136
	v_fma_f32 v137, -v135, v139, v138
	v_fmac_f32_e32 v139, v137, v136
	v_fma_f32 v135, -v135, v139, v138
	v_div_fmas_f32 v135, v135, v136, v139
	v_div_scale_f32 v144, vcc, v44, v140, v44
	v_mul_f32_e32 v145, v144, v142
	v_fma_f32 v143, -v141, v145, v144
	v_fmac_f32_e32 v145, v143, v142
	v_fma_f32 v141, -v141, v145, v144
	v_div_fmas_f32 v141, v141, v142, v145
	v_div_fixup_f32 v134, v135, v134, v60
	v_div_fixup_f32 v140, v141, v140, v44
	v_bfe_u32 v135, v134, 16, 1
	v_bfe_u32 v141, v140, 16, 1
	v_add3_u32 v134, v134, v135, s1
	v_add3_u32 v140, v140, v141, s1
	ds_write_b16_d16_hi v147, v134 offset:4896
	ds_write_b16_d16_hi v147, v140 offset:5024
	v_mul_f32_e32 v134, 0xbfb8aa3b, v61
	v_mul_f32_e32 v140, 0xbfb8aa3b, v45
	v_exp_f32_e32 v134, v134
	v_exp_f32_e32 v140, v140
	v_add_f32_e32 v134, 1.0, v134
	v_add_f32_e32 v140, 1.0, v140
	v_div_scale_f32 v135, s[2:3], v134, v134, v61
	v_div_scale_f32 v141, s[2:3], v140, v140, v45
	v_rcp_f32_e32 v136, v135
	v_rcp_f32_e32 v142, v141
	v_fma_f32 v137, -v135, v136, 1.0
	v_fma_f32 v143, -v141, v142, 1.0
	v_fmac_f32_e32 v136, v137, v136
	v_fmac_f32_e32 v142, v143, v142
	v_div_scale_f32 v138, vcc, v61, v134, v61
	v_mul_f32_e32 v139, v138, v136
	v_fma_f32 v137, -v135, v139, v138
	v_fmac_f32_e32 v139, v137, v136
	v_fma_f32 v135, -v135, v139, v138
	v_div_fmas_f32 v135, v135, v136, v139
	v_div_scale_f32 v144, vcc, v45, v140, v45
	v_mul_f32_e32 v145, v144, v142
	v_fma_f32 v143, -v141, v145, v144
	v_fmac_f32_e32 v145, v143, v142
	v_fma_f32 v141, -v141, v145, v144
	v_div_fmas_f32 v141, v141, v142, v145
	v_div_fixup_f32 v134, v135, v134, v61
	v_div_fixup_f32 v140, v141, v140, v45
	v_bfe_u32 v135, v134, 16, 1
	v_bfe_u32 v141, v140, 16, 1
	v_add3_u32 v134, v134, v135, s1
	v_add3_u32 v140, v140, v141, s1
	ds_write_b16_d16_hi v147, v134 offset:5168
	ds_write_b16_d16_hi v147, v140 offset:5296
	v_mul_f32_e32 v134, 0xbfb8aa3b, v62
	v_mul_f32_e32 v140, 0xbfb8aa3b, v46
	v_exp_f32_e32 v134, v134
	v_exp_f32_e32 v140, v140
	v_add_f32_e32 v134, 1.0, v134
	v_add_f32_e32 v140, 1.0, v140
	v_div_scale_f32 v135, s[2:3], v134, v134, v62
	v_div_scale_f32 v141, s[2:3], v140, v140, v46
	v_rcp_f32_e32 v136, v135
	v_rcp_f32_e32 v142, v141
	v_fma_f32 v137, -v135, v136, 1.0
	v_fma_f32 v143, -v141, v142, 1.0
	v_fmac_f32_e32 v136, v137, v136
	v_fmac_f32_e32 v142, v143, v142
	v_div_scale_f32 v138, vcc, v62, v134, v62
	v_mul_f32_e32 v139, v138, v136
	v_fma_f32 v137, -v135, v139, v138
	v_fmac_f32_e32 v139, v137, v136
	v_fma_f32 v135, -v135, v139, v138
	v_div_fmas_f32 v135, v135, v136, v139
	v_div_scale_f32 v144, vcc, v46, v140, v46
	v_mul_f32_e32 v145, v144, v142
	v_fma_f32 v143, -v141, v145, v144
	v_fmac_f32_e32 v145, v143, v142
	v_fma_f32 v141, -v141, v145, v144
	v_div_fmas_f32 v141, v141, v142, v145
	v_div_fixup_f32 v134, v135, v134, v62
	v_div_fixup_f32 v140, v141, v140, v46
	v_bfe_u32 v135, v134, 16, 1
	v_bfe_u32 v141, v140, 16, 1
	v_add3_u32 v134, v134, v135, s1
	v_add3_u32 v140, v140, v141, s1
	ds_write_b16_d16_hi v147, v134 offset:6528
	ds_write_b16_d16_hi v147, v140 offset:6656
	v_mul_f32_e32 v134, 0xbfb8aa3b, v63
	v_mul_f32_e32 v140, 0xbfb8aa3b, v47
	v_exp_f32_e32 v134, v134
	v_exp_f32_e32 v140, v140
	v_add_f32_e32 v134, 1.0, v134
	v_add_f32_e32 v140, 1.0, v140
	v_div_scale_f32 v135, s[2:3], v134, v134, v63
	v_div_scale_f32 v141, s[2:3], v140, v140, v47
	v_rcp_f32_e32 v136, v135
	v_rcp_f32_e32 v142, v141
	v_fma_f32 v137, -v135, v136, 1.0
	v_fma_f32 v143, -v141, v142, 1.0
	v_fmac_f32_e32 v136, v137, v136
	v_fmac_f32_e32 v142, v143, v142
	v_div_scale_f32 v138, vcc, v63, v134, v63
	v_mul_f32_e32 v139, v138, v136
	v_fma_f32 v137, -v135, v139, v138
	v_fmac_f32_e32 v139, v137, v136
	v_fma_f32 v135, -v135, v139, v138
	v_div_fmas_f32 v135, v135, v136, v139
	v_div_scale_f32 v144, vcc, v47, v140, v47
	v_mul_f32_e32 v145, v144, v142
	v_fma_f32 v143, -v141, v145, v144
	v_fmac_f32_e32 v145, v143, v142
	v_fma_f32 v141, -v141, v145, v144
	v_div_fmas_f32 v141, v141, v142, v145
	v_div_fixup_f32 v134, v135, v134, v63
	v_div_fixup_f32 v140, v141, v140, v47
	v_bfe_u32 v135, v134, 16, 1
	v_bfe_u32 v141, v140, 16, 1
	v_add3_u32 v134, v134, v135, s1
	v_add3_u32 v140, v140, v141, s1
	ds_write_b16_d16_hi v147, v134 offset:6800
	ds_write_b16_d16_hi v147, v140 offset:6928
	v_mul_f32_e32 v134, 0xbfb8aa3b, v64
	v_mul_f32_e32 v140, 0xbfb8aa3b, v48
	v_exp_f32_e32 v134, v134
	v_exp_f32_e32 v140, v140
	v_add_f32_e32 v134, 1.0, v134
	v_add_f32_e32 v140, 1.0, v140
	v_div_scale_f32 v135, s[2:3], v134, v134, v64
	v_div_scale_f32 v141, s[2:3], v140, v140, v48
	v_rcp_f32_e32 v136, v135
	v_rcp_f32_e32 v142, v141
	v_fma_f32 v137, -v135, v136, 1.0
	v_fma_f32 v143, -v141, v142, 1.0
	v_fmac_f32_e32 v136, v137, v136
	v_fmac_f32_e32 v142, v143, v142
	v_div_scale_f32 v138, vcc, v64, v134, v64
	v_mul_f32_e32 v139, v138, v136
	v_fma_f32 v137, -v135, v139, v138
	v_fmac_f32_e32 v139, v137, v136
	v_fma_f32 v135, -v135, v139, v138
	v_div_fmas_f32 v135, v135, v136, v139
	v_div_scale_f32 v144, vcc, v48, v140, v48
	v_mul_f32_e32 v145, v144, v142
	v_fma_f32 v143, -v141, v145, v144
	v_fmac_f32_e32 v145, v143, v142
	v_fma_f32 v141, -v141, v145, v144
	v_div_fmas_f32 v141, v141, v142, v145
	v_div_fixup_f32 v134, v135, v134, v64
	v_div_fixup_f32 v140, v141, v140, v48
	v_bfe_u32 v135, v134, 16, 1
	v_bfe_u32 v141, v140, 16, 1
	v_add3_u32 v134, v134, v135, s1
	v_add3_u32 v140, v140, v141, s1
	ds_write_b16_d16_hi v147, v134 offset:7072
	ds_write_b16_d16_hi v147, v140 offset:7200
	v_mul_f32_e32 v134, 0xbfb8aa3b, v65
	v_mul_f32_e32 v140, 0xbfb8aa3b, v49
	v_exp_f32_e32 v134, v134
	v_exp_f32_e32 v140, v140
	v_add_f32_e32 v134, 1.0, v134
	v_add_f32_e32 v140, 1.0, v140
	v_div_scale_f32 v135, s[2:3], v134, v134, v65
	v_div_scale_f32 v141, s[2:3], v140, v140, v49
	v_rcp_f32_e32 v136, v135
	v_rcp_f32_e32 v142, v141
	v_fma_f32 v137, -v135, v136, 1.0
	v_fma_f32 v143, -v141, v142, 1.0
	v_fmac_f32_e32 v136, v137, v136
	v_fmac_f32_e32 v142, v143, v142
	v_div_scale_f32 v138, vcc, v65, v134, v65
	v_mul_f32_e32 v139, v138, v136
	v_fma_f32 v137, -v135, v139, v138
	v_fmac_f32_e32 v139, v137, v136
	v_fma_f32 v135, -v135, v139, v138
	v_div_fmas_f32 v135, v135, v136, v139
	v_div_scale_f32 v144, vcc, v49, v140, v49
	v_mul_f32_e32 v145, v144, v142
	v_fma_f32 v143, -v141, v145, v144
	v_fmac_f32_e32 v145, v143, v142
	v_fma_f32 v141, -v141, v145, v144
	v_div_fmas_f32 v141, v141, v142, v145
	v_div_fixup_f32 v134, v135, v134, v65
	v_div_fixup_f32 v140, v141, v140, v49
	v_bfe_u32 v135, v134, 16, 1
	v_bfe_u32 v141, v140, 16, 1
	v_add3_u32 v134, v134, v135, s1
	v_add3_u32 v140, v140, v141, s1
	ds_write_b16_d16_hi v147, v134 offset:7344
	ds_write_b16_d16_hi v147, v140 offset:7472
	v_mul_f32_e32 v134, 0xbfb8aa3b, v16
	v_mul_f32_e32 v140, 0xbfb8aa3b, v0
	v_exp_f32_e32 v134, v134
	v_exp_f32_e32 v140, v140
	v_add_f32_e32 v134, 1.0, v134
	v_add_f32_e32 v140, 1.0, v140
	v_div_scale_f32 v135, s[2:3], v134, v134, v16
	v_div_scale_f32 v141, s[2:3], v140, v140, v0
	v_rcp_f32_e32 v136, v135
	v_rcp_f32_e32 v142, v141
	v_fma_f32 v137, -v135, v136, 1.0
	v_fma_f32 v143, -v141, v142, 1.0
	v_fmac_f32_e32 v136, v137, v136
	v_fmac_f32_e32 v142, v143, v142
	v_div_scale_f32 v138, vcc, v16, v134, v16
	v_mul_f32_e32 v139, v138, v136
	v_fma_f32 v137, -v135, v139, v138
	v_fmac_f32_e32 v139, v137, v136
	v_fma_f32 v135, -v135, v139, v138
	v_div_fmas_f32 v135, v135, v136, v139
	v_div_scale_f32 v144, vcc, v0, v140, v0
	v_mul_f32_e32 v145, v144, v142
	v_fma_f32 v143, -v141, v145, v144
	v_fmac_f32_e32 v145, v143, v142
	v_fma_f32 v141, -v141, v145, v144
	v_div_fmas_f32 v141, v141, v142, v145
	v_div_fixup_f32 v134, v135, v134, v16
	v_div_fixup_f32 v140, v141, v140, v0
	v_bfe_u32 v135, v134, 16, 1
	v_bfe_u32 v141, v140, 16, 1
	v_add3_u32 v134, v134, v135, s1
	v_add3_u32 v140, v140, v141, s1
	ds_write_b16_d16_hi v147, v134 offset:64
	ds_write_b16_d16_hi v147, v140 offset:192
	v_mul_f32_e32 v134, 0xbfb8aa3b, v17
	v_mul_f32_e32 v140, 0xbfb8aa3b, v1
	v_exp_f32_e32 v134, v134
	v_exp_f32_e32 v140, v140
	v_add_f32_e32 v134, 1.0, v134
	v_add_f32_e32 v140, 1.0, v140
	v_div_scale_f32 v135, s[2:3], v134, v134, v17
	v_div_scale_f32 v141, s[2:3], v140, v140, v1
	v_rcp_f32_e32 v136, v135
	v_rcp_f32_e32 v142, v141
	v_fma_f32 v137, -v135, v136, 1.0
	v_fma_f32 v143, -v141, v142, 1.0
	v_fmac_f32_e32 v136, v137, v136
	v_fmac_f32_e32 v142, v143, v142
	v_div_scale_f32 v138, vcc, v17, v134, v17
	v_mul_f32_e32 v139, v138, v136
	v_fma_f32 v137, -v135, v139, v138
	v_fmac_f32_e32 v139, v137, v136
	v_fma_f32 v135, -v135, v139, v138
	v_div_fmas_f32 v135, v135, v136, v139
	v_div_scale_f32 v144, vcc, v1, v140, v1
	v_mul_f32_e32 v145, v144, v142
	v_fma_f32 v143, -v141, v145, v144
	v_fmac_f32_e32 v145, v143, v142
	v_fma_f32 v141, -v141, v145, v144
	v_div_fmas_f32 v141, v141, v142, v145
	v_div_fixup_f32 v134, v135, v134, v17
	v_div_fixup_f32 v140, v141, v140, v1
	v_bfe_u32 v135, v134, 16, 1
	v_bfe_u32 v141, v140, 16, 1
	v_add3_u32 v134, v134, v135, s1
	v_add3_u32 v140, v140, v141, s1
	ds_write_b16_d16_hi v147, v134 offset:336
	ds_write_b16_d16_hi v147, v140 offset:464
	v_mul_f32_e32 v134, 0xbfb8aa3b, v18
	v_mul_f32_e32 v140, 0xbfb8aa3b, v2
	v_exp_f32_e32 v134, v134
	v_exp_f32_e32 v140, v140
	v_add_f32_e32 v134, 1.0, v134
	v_add_f32_e32 v140, 1.0, v140
	v_div_scale_f32 v135, s[2:3], v134, v134, v18
	v_div_scale_f32 v141, s[2:3], v140, v140, v2
	v_rcp_f32_e32 v136, v135
	v_rcp_f32_e32 v142, v141
	v_fma_f32 v137, -v135, v136, 1.0
	v_fma_f32 v143, -v141, v142, 1.0
	v_fmac_f32_e32 v136, v137, v136
	v_fmac_f32_e32 v142, v143, v142
	v_div_scale_f32 v138, vcc, v18, v134, v18
	v_mul_f32_e32 v139, v138, v136
	v_fma_f32 v137, -v135, v139, v138
	v_fmac_f32_e32 v139, v137, v136
	v_fma_f32 v135, -v135, v139, v138
	v_div_fmas_f32 v135, v135, v136, v139
	v_div_scale_f32 v144, vcc, v2, v140, v2
	v_mul_f32_e32 v145, v144, v142
	v_fma_f32 v143, -v141, v145, v144
	v_fmac_f32_e32 v145, v143, v142
	v_fma_f32 v141, -v141, v145, v144
	v_div_fmas_f32 v141, v141, v142, v145
	v_div_fixup_f32 v134, v135, v134, v18
	v_div_fixup_f32 v140, v141, v140, v2
	v_bfe_u32 v135, v134, 16, 1
	v_bfe_u32 v141, v140, 16, 1
	v_add3_u32 v134, v134, v135, s1
	v_add3_u32 v140, v140, v141, s1
	ds_write_b16_d16_hi v147, v134 offset:608
	ds_write_b16_d16_hi v147, v140 offset:736
	v_mul_f32_e32 v134, 0xbfb8aa3b, v19
	v_mul_f32_e32 v140, 0xbfb8aa3b, v3
	v_exp_f32_e32 v134, v134
	v_exp_f32_e32 v140, v140
	v_add_f32_e32 v134, 1.0, v134
	v_add_f32_e32 v140, 1.0, v140
	v_div_scale_f32 v135, s[2:3], v134, v134, v19
	v_div_scale_f32 v141, s[2:3], v140, v140, v3
	v_rcp_f32_e32 v136, v135
	v_rcp_f32_e32 v142, v141
	v_fma_f32 v137, -v135, v136, 1.0
	v_fma_f32 v143, -v141, v142, 1.0
	v_fmac_f32_e32 v136, v137, v136
	v_fmac_f32_e32 v142, v143, v142
	v_div_scale_f32 v138, vcc, v19, v134, v19
	v_mul_f32_e32 v139, v138, v136
	v_fma_f32 v137, -v135, v139, v138
	v_fmac_f32_e32 v139, v137, v136
	v_fma_f32 v135, -v135, v139, v138
	v_div_fmas_f32 v135, v135, v136, v139
	v_div_scale_f32 v144, vcc, v3, v140, v3
	v_mul_f32_e32 v145, v144, v142
	v_fma_f32 v143, -v141, v145, v144
	v_fmac_f32_e32 v145, v143, v142
	v_fma_f32 v141, -v141, v145, v144
	v_div_fmas_f32 v141, v141, v142, v145
	v_div_fixup_f32 v134, v135, v134, v19
	v_div_fixup_f32 v140, v141, v140, v3
	v_bfe_u32 v135, v134, 16, 1
	v_bfe_u32 v141, v140, 16, 1
	v_add3_u32 v134, v134, v135, s1
	v_add3_u32 v140, v140, v141, s1
	ds_write_b16_d16_hi v147, v134 offset:880
	ds_write_b16_d16_hi v147, v140 offset:1008
	v_mul_f32_e32 v134, 0xbfb8aa3b, v20
	v_mul_f32_e32 v140, 0xbfb8aa3b, v4
	v_exp_f32_e32 v134, v134
	v_exp_f32_e32 v140, v140
	v_add_f32_e32 v134, 1.0, v134
	v_add_f32_e32 v140, 1.0, v140
	v_div_scale_f32 v135, s[2:3], v134, v134, v20
	v_div_scale_f32 v141, s[2:3], v140, v140, v4
	v_rcp_f32_e32 v136, v135
	v_rcp_f32_e32 v142, v141
	v_fma_f32 v137, -v135, v136, 1.0
	v_fma_f32 v143, -v141, v142, 1.0
	v_fmac_f32_e32 v136, v137, v136
	v_fmac_f32_e32 v142, v143, v142
	v_div_scale_f32 v138, vcc, v20, v134, v20
	v_mul_f32_e32 v139, v138, v136
	v_fma_f32 v137, -v135, v139, v138
	v_fmac_f32_e32 v139, v137, v136
	v_fma_f32 v135, -v135, v139, v138
	v_div_fmas_f32 v135, v135, v136, v139
	v_div_scale_f32 v144, vcc, v4, v140, v4
	v_mul_f32_e32 v145, v144, v142
	v_fma_f32 v143, -v141, v145, v144
	v_fmac_f32_e32 v145, v143, v142
	v_fma_f32 v141, -v141, v145, v144
	v_div_fmas_f32 v141, v141, v142, v145
	v_div_fixup_f32 v134, v135, v134, v20
	v_div_fixup_f32 v140, v141, v140, v4
	v_bfe_u32 v135, v134, 16, 1
	v_bfe_u32 v141, v140, 16, 1
	v_add3_u32 v134, v134, v135, s1
	v_add3_u32 v140, v140, v141, s1
	ds_write_b16_d16_hi v147, v134 offset:2240
	ds_write_b16_d16_hi v147, v140 offset:2368
	v_mul_f32_e32 v134, 0xbfb8aa3b, v21
	v_mul_f32_e32 v140, 0xbfb8aa3b, v5
	v_exp_f32_e32 v134, v134
	v_exp_f32_e32 v140, v140
	v_add_f32_e32 v134, 1.0, v134
	v_add_f32_e32 v140, 1.0, v140
	v_div_scale_f32 v135, s[2:3], v134, v134, v21
	v_div_scale_f32 v141, s[2:3], v140, v140, v5
	v_rcp_f32_e32 v136, v135
	v_rcp_f32_e32 v142, v141
	v_fma_f32 v137, -v135, v136, 1.0
	v_fma_f32 v143, -v141, v142, 1.0
	v_fmac_f32_e32 v136, v137, v136
	v_fmac_f32_e32 v142, v143, v142
	v_div_scale_f32 v138, vcc, v21, v134, v21
	v_mul_f32_e32 v139, v138, v136
	v_fma_f32 v137, -v135, v139, v138
	v_fmac_f32_e32 v139, v137, v136
	v_fma_f32 v135, -v135, v139, v138
	v_div_fmas_f32 v135, v135, v136, v139
	v_div_scale_f32 v144, vcc, v5, v140, v5
	v_mul_f32_e32 v145, v144, v142
	v_fma_f32 v143, -v141, v145, v144
	v_fmac_f32_e32 v145, v143, v142
	v_fma_f32 v141, -v141, v145, v144
	v_div_fmas_f32 v141, v141, v142, v145
	v_div_fixup_f32 v134, v135, v134, v21
	v_div_fixup_f32 v140, v141, v140, v5
	v_bfe_u32 v135, v134, 16, 1
	v_bfe_u32 v141, v140, 16, 1
	v_add3_u32 v134, v134, v135, s1
	v_add3_u32 v140, v140, v141, s1
	ds_write_b16_d16_hi v147, v134 offset:2512
	ds_write_b16_d16_hi v147, v140 offset:2640
	v_mul_f32_e32 v134, 0xbfb8aa3b, v22
	v_mul_f32_e32 v140, 0xbfb8aa3b, v6
	v_exp_f32_e32 v134, v134
	v_exp_f32_e32 v140, v140
	v_add_f32_e32 v134, 1.0, v134
	v_add_f32_e32 v140, 1.0, v140
	v_div_scale_f32 v135, s[2:3], v134, v134, v22
	v_div_scale_f32 v141, s[2:3], v140, v140, v6
	v_rcp_f32_e32 v136, v135
	v_rcp_f32_e32 v142, v141
	v_fma_f32 v137, -v135, v136, 1.0
	v_fma_f32 v143, -v141, v142, 1.0
	v_fmac_f32_e32 v136, v137, v136
	v_fmac_f32_e32 v142, v143, v142
	v_div_scale_f32 v138, vcc, v22, v134, v22
	v_mul_f32_e32 v139, v138, v136
	v_fma_f32 v137, -v135, v139, v138
	v_fmac_f32_e32 v139, v137, v136
	v_fma_f32 v135, -v135, v139, v138
	v_div_fmas_f32 v135, v135, v136, v139
	v_div_scale_f32 v144, vcc, v6, v140, v6
	v_mul_f32_e32 v145, v144, v142
	v_fma_f32 v143, -v141, v145, v144
	v_fmac_f32_e32 v145, v143, v142
	v_fma_f32 v141, -v141, v145, v144
	v_div_fmas_f32 v141, v141, v142, v145
	v_div_fixup_f32 v134, v135, v134, v22
	v_div_fixup_f32 v140, v141, v140, v6
	v_bfe_u32 v135, v134, 16, 1
	v_bfe_u32 v141, v140, 16, 1
	v_add3_u32 v134, v134, v135, s1
	v_add3_u32 v140, v140, v141, s1
	ds_write_b16_d16_hi v147, v134 offset:2784
	ds_write_b16_d16_hi v147, v140 offset:2912
	v_mul_f32_e32 v134, 0xbfb8aa3b, v23
	v_mul_f32_e32 v140, 0xbfb8aa3b, v7
	v_exp_f32_e32 v134, v134
	v_exp_f32_e32 v140, v140
	v_add_f32_e32 v134, 1.0, v134
	v_add_f32_e32 v140, 1.0, v140
	v_div_scale_f32 v135, s[2:3], v134, v134, v23
	v_div_scale_f32 v141, s[2:3], v140, v140, v7
	v_rcp_f32_e32 v136, v135
	v_rcp_f32_e32 v142, v141
	v_fma_f32 v137, -v135, v136, 1.0
	v_fma_f32 v143, -v141, v142, 1.0
	v_fmac_f32_e32 v136, v137, v136
	v_fmac_f32_e32 v142, v143, v142
	v_div_scale_f32 v138, vcc, v23, v134, v23
	v_mul_f32_e32 v139, v138, v136
	v_fma_f32 v137, -v135, v139, v138
	v_fmac_f32_e32 v139, v137, v136
	v_fma_f32 v135, -v135, v139, v138
	v_div_fmas_f32 v135, v135, v136, v139
	v_div_scale_f32 v144, vcc, v7, v140, v7
	v_mul_f32_e32 v145, v144, v142
	v_fma_f32 v143, -v141, v145, v144
	v_fmac_f32_e32 v145, v143, v142
	v_fma_f32 v141, -v141, v145, v144
	v_div_fmas_f32 v141, v141, v142, v145
	v_div_fixup_f32 v134, v135, v134, v23
	v_div_fixup_f32 v140, v141, v140, v7
	v_bfe_u32 v135, v134, 16, 1
	v_bfe_u32 v141, v140, 16, 1
	v_add3_u32 v134, v134, v135, s1
	v_add3_u32 v140, v140, v141, s1
	ds_write_b16_d16_hi v147, v134 offset:3056
	ds_write_b16_d16_hi v147, v140 offset:3184
	v_mul_f32_e32 v134, 0xbfb8aa3b, v24
	v_mul_f32_e32 v140, 0xbfb8aa3b, v8
	v_exp_f32_e32 v134, v134
	v_exp_f32_e32 v140, v140
	v_add_f32_e32 v134, 1.0, v134
	v_add_f32_e32 v140, 1.0, v140
	v_div_scale_f32 v135, s[2:3], v134, v134, v24
	v_div_scale_f32 v141, s[2:3], v140, v140, v8
	v_rcp_f32_e32 v136, v135
	v_rcp_f32_e32 v142, v141
	v_fma_f32 v137, -v135, v136, 1.0
	v_fma_f32 v143, -v141, v142, 1.0
	v_fmac_f32_e32 v136, v137, v136
	v_fmac_f32_e32 v142, v143, v142
	v_div_scale_f32 v138, vcc, v24, v134, v24
	v_mul_f32_e32 v139, v138, v136
	v_fma_f32 v137, -v135, v139, v138
	v_fmac_f32_e32 v139, v137, v136
	v_fma_f32 v135, -v135, v139, v138
	v_div_fmas_f32 v135, v135, v136, v139
	v_div_scale_f32 v144, vcc, v8, v140, v8
	v_mul_f32_e32 v145, v144, v142
	v_fma_f32 v143, -v141, v145, v144
	v_fmac_f32_e32 v145, v143, v142
	v_fma_f32 v141, -v141, v145, v144
	v_div_fmas_f32 v141, v141, v142, v145
	v_div_fixup_f32 v134, v135, v134, v24
	v_div_fixup_f32 v140, v141, v140, v8
	v_bfe_u32 v135, v134, 16, 1
	v_bfe_u32 v141, v140, 16, 1
	v_add3_u32 v134, v134, v135, s1
	v_add3_u32 v140, v140, v141, s1
	ds_write_b16_d16_hi v147, v134 offset:4416
	ds_write_b16_d16_hi v147, v140 offset:4544
	v_mul_f32_e32 v134, 0xbfb8aa3b, v25
	v_mul_f32_e32 v140, 0xbfb8aa3b, v9
	v_exp_f32_e32 v134, v134
	v_exp_f32_e32 v140, v140
	v_add_f32_e32 v134, 1.0, v134
	v_add_f32_e32 v140, 1.0, v140
	v_div_scale_f32 v135, s[2:3], v134, v134, v25
	v_div_scale_f32 v141, s[2:3], v140, v140, v9
	v_rcp_f32_e32 v136, v135
	v_rcp_f32_e32 v142, v141
	v_fma_f32 v137, -v135, v136, 1.0
	v_fma_f32 v143, -v141, v142, 1.0
	v_fmac_f32_e32 v136, v137, v136
	v_fmac_f32_e32 v142, v143, v142
	v_div_scale_f32 v138, vcc, v25, v134, v25
	v_mul_f32_e32 v139, v138, v136
	v_fma_f32 v137, -v135, v139, v138
	v_fmac_f32_e32 v139, v137, v136
	v_fma_f32 v135, -v135, v139, v138
	v_div_fmas_f32 v135, v135, v136, v139
	v_div_scale_f32 v144, vcc, v9, v140, v9
	v_mul_f32_e32 v145, v144, v142
	v_fma_f32 v143, -v141, v145, v144
	v_fmac_f32_e32 v145, v143, v142
	v_fma_f32 v141, -v141, v145, v144
	v_div_fmas_f32 v141, v141, v142, v145
	v_div_fixup_f32 v134, v135, v134, v25
	v_div_fixup_f32 v140, v141, v140, v9
	v_bfe_u32 v135, v134, 16, 1
	v_bfe_u32 v141, v140, 16, 1
	v_add3_u32 v134, v134, v135, s1
	v_add3_u32 v140, v140, v141, s1
	ds_write_b16_d16_hi v147, v134 offset:4688
	ds_write_b16_d16_hi v147, v140 offset:4816
	v_mul_f32_e32 v134, 0xbfb8aa3b, v26
	v_mul_f32_e32 v140, 0xbfb8aa3b, v10
	v_exp_f32_e32 v134, v134
	v_exp_f32_e32 v140, v140
	v_add_f32_e32 v134, 1.0, v134
	v_add_f32_e32 v140, 1.0, v140
	v_div_scale_f32 v135, s[2:3], v134, v134, v26
	v_div_scale_f32 v141, s[2:3], v140, v140, v10
	v_rcp_f32_e32 v136, v135
	v_rcp_f32_e32 v142, v141
	v_fma_f32 v137, -v135, v136, 1.0
	v_fma_f32 v143, -v141, v142, 1.0
	v_fmac_f32_e32 v136, v137, v136
	v_fmac_f32_e32 v142, v143, v142
	v_div_scale_f32 v138, vcc, v26, v134, v26
	v_mul_f32_e32 v139, v138, v136
	v_fma_f32 v137, -v135, v139, v138
	v_fmac_f32_e32 v139, v137, v136
	v_fma_f32 v135, -v135, v139, v138
	v_div_fmas_f32 v135, v135, v136, v139
	v_div_scale_f32 v144, vcc, v10, v140, v10
	v_mul_f32_e32 v145, v144, v142
	v_fma_f32 v143, -v141, v145, v144
	v_fmac_f32_e32 v145, v143, v142
	v_fma_f32 v141, -v141, v145, v144
	v_div_fmas_f32 v141, v141, v142, v145
	v_div_fixup_f32 v134, v135, v134, v26
	v_div_fixup_f32 v140, v141, v140, v10
	v_bfe_u32 v135, v134, 16, 1
	v_bfe_u32 v141, v140, 16, 1
	v_add3_u32 v134, v134, v135, s1
	v_add3_u32 v140, v140, v141, s1
	ds_write_b16_d16_hi v147, v134 offset:4960
	ds_write_b16_d16_hi v147, v140 offset:5088
	v_mul_f32_e32 v134, 0xbfb8aa3b, v27
	v_mul_f32_e32 v140, 0xbfb8aa3b, v11
	v_exp_f32_e32 v134, v134
	v_exp_f32_e32 v140, v140
	v_add_f32_e32 v134, 1.0, v134
	v_add_f32_e32 v140, 1.0, v140
	v_div_scale_f32 v135, s[2:3], v134, v134, v27
	v_div_scale_f32 v141, s[2:3], v140, v140, v11
	v_rcp_f32_e32 v136, v135
	v_rcp_f32_e32 v142, v141
	v_fma_f32 v137, -v135, v136, 1.0
	v_fma_f32 v143, -v141, v142, 1.0
	v_fmac_f32_e32 v136, v137, v136
	v_fmac_f32_e32 v142, v143, v142
	v_div_scale_f32 v138, vcc, v27, v134, v27
	v_mul_f32_e32 v139, v138, v136
	v_fma_f32 v137, -v135, v139, v138
	v_fmac_f32_e32 v139, v137, v136
	v_fma_f32 v135, -v135, v139, v138
	v_div_fmas_f32 v135, v135, v136, v139
	v_div_scale_f32 v144, vcc, v11, v140, v11
	v_mul_f32_e32 v145, v144, v142
	v_fma_f32 v143, -v141, v145, v144
	v_fmac_f32_e32 v145, v143, v142
	v_fma_f32 v141, -v141, v145, v144
	v_div_fmas_f32 v141, v141, v142, v145
	v_div_fixup_f32 v134, v135, v134, v27
	v_div_fixup_f32 v140, v141, v140, v11
	v_bfe_u32 v135, v134, 16, 1
	v_bfe_u32 v141, v140, 16, 1
	v_add3_u32 v134, v134, v135, s1
	v_add3_u32 v140, v140, v141, s1
	ds_write_b16_d16_hi v147, v134 offset:5232
	ds_write_b16_d16_hi v147, v140 offset:5360
	v_mul_f32_e32 v134, 0xbfb8aa3b, v28
	v_mul_f32_e32 v140, 0xbfb8aa3b, v12
	v_exp_f32_e32 v134, v134
	v_exp_f32_e32 v140, v140
	v_add_f32_e32 v134, 1.0, v134
	v_add_f32_e32 v140, 1.0, v140
	v_div_scale_f32 v135, s[2:3], v134, v134, v28
	v_div_scale_f32 v141, s[2:3], v140, v140, v12
	v_rcp_f32_e32 v136, v135
	v_rcp_f32_e32 v142, v141
	v_fma_f32 v137, -v135, v136, 1.0
	v_fma_f32 v143, -v141, v142, 1.0
	v_fmac_f32_e32 v136, v137, v136
	v_fmac_f32_e32 v142, v143, v142
	v_div_scale_f32 v138, vcc, v28, v134, v28
	v_mul_f32_e32 v139, v138, v136
	v_fma_f32 v137, -v135, v139, v138
	v_fmac_f32_e32 v139, v137, v136
	v_fma_f32 v135, -v135, v139, v138
	v_div_fmas_f32 v135, v135, v136, v139
	v_div_scale_f32 v144, vcc, v12, v140, v12
	v_mul_f32_e32 v145, v144, v142
	v_fma_f32 v143, -v141, v145, v144
	v_fmac_f32_e32 v145, v143, v142
	v_fma_f32 v141, -v141, v145, v144
	v_div_fmas_f32 v141, v141, v142, v145
	v_div_fixup_f32 v134, v135, v134, v28
	v_div_fixup_f32 v140, v141, v140, v12
	v_bfe_u32 v135, v134, 16, 1
	v_bfe_u32 v141, v140, 16, 1
	v_add3_u32 v134, v134, v135, s1
	v_add3_u32 v140, v140, v141, s1
	ds_write_b16_d16_hi v147, v134 offset:6592
	ds_write_b16_d16_hi v147, v140 offset:6720
	v_mul_f32_e32 v134, 0xbfb8aa3b, v29
	v_mul_f32_e32 v140, 0xbfb8aa3b, v13
	v_exp_f32_e32 v134, v134
	v_exp_f32_e32 v140, v140
	v_add_f32_e32 v134, 1.0, v134
	v_add_f32_e32 v140, 1.0, v140
	v_div_scale_f32 v135, s[2:3], v134, v134, v29
	v_div_scale_f32 v141, s[2:3], v140, v140, v13
	v_rcp_f32_e32 v136, v135
	v_rcp_f32_e32 v142, v141
	v_fma_f32 v137, -v135, v136, 1.0
	v_fma_f32 v143, -v141, v142, 1.0
	v_fmac_f32_e32 v136, v137, v136
	v_fmac_f32_e32 v142, v143, v142
	v_div_scale_f32 v138, vcc, v29, v134, v29
	v_mul_f32_e32 v139, v138, v136
	v_fma_f32 v137, -v135, v139, v138
	v_fmac_f32_e32 v139, v137, v136
	v_fma_f32 v135, -v135, v139, v138
	v_div_fmas_f32 v135, v135, v136, v139
	v_div_scale_f32 v144, vcc, v13, v140, v13
	v_mul_f32_e32 v145, v144, v142
	v_fma_f32 v143, -v141, v145, v144
	v_fmac_f32_e32 v145, v143, v142
	v_fma_f32 v141, -v141, v145, v144
	v_div_fmas_f32 v141, v141, v142, v145
	v_div_fixup_f32 v134, v135, v134, v29
	v_div_fixup_f32 v140, v141, v140, v13
	v_bfe_u32 v135, v134, 16, 1
	v_bfe_u32 v141, v140, 16, 1
	v_add3_u32 v134, v134, v135, s1
	v_add3_u32 v140, v140, v141, s1
	ds_write_b16_d16_hi v147, v134 offset:6864
	ds_write_b16_d16_hi v147, v140 offset:6992
	v_mul_f32_e32 v134, 0xbfb8aa3b, v30
	v_mul_f32_e32 v140, 0xbfb8aa3b, v14
	v_exp_f32_e32 v134, v134
	v_exp_f32_e32 v140, v140
	v_add_f32_e32 v134, 1.0, v134
	v_add_f32_e32 v140, 1.0, v140
	v_div_scale_f32 v135, s[2:3], v134, v134, v30
	v_div_scale_f32 v141, s[2:3], v140, v140, v14
	v_rcp_f32_e32 v136, v135
	v_rcp_f32_e32 v142, v141
	v_fma_f32 v137, -v135, v136, 1.0
	v_fma_f32 v143, -v141, v142, 1.0
	v_fmac_f32_e32 v136, v137, v136
	v_fmac_f32_e32 v142, v143, v142
	v_div_scale_f32 v138, vcc, v30, v134, v30
	v_mul_f32_e32 v139, v138, v136
	v_fma_f32 v137, -v135, v139, v138
	v_fmac_f32_e32 v139, v137, v136
	v_fma_f32 v135, -v135, v139, v138
	v_div_fmas_f32 v135, v135, v136, v139
	v_div_scale_f32 v144, vcc, v14, v140, v14
	v_mul_f32_e32 v145, v144, v142
	v_fma_f32 v143, -v141, v145, v144
	v_fmac_f32_e32 v145, v143, v142
	v_fma_f32 v141, -v141, v145, v144
	v_div_fmas_f32 v141, v141, v142, v145
	v_div_fixup_f32 v134, v135, v134, v30
	v_div_fixup_f32 v140, v141, v140, v14
	v_bfe_u32 v135, v134, 16, 1
	v_bfe_u32 v141, v140, 16, 1
	v_add3_u32 v134, v134, v135, s1
	v_add3_u32 v140, v140, v141, s1
	ds_write_b16_d16_hi v147, v134 offset:7136
	ds_write_b16_d16_hi v147, v140 offset:7264
	v_mul_f32_e32 v134, 0xbfb8aa3b, v31
	v_mul_f32_e32 v140, 0xbfb8aa3b, v15
	v_exp_f32_e32 v134, v134
	v_exp_f32_e32 v140, v140
	v_add_f32_e32 v134, 1.0, v134
	v_add_f32_e32 v140, 1.0, v140
	v_div_scale_f32 v135, s[2:3], v134, v134, v31
	v_div_scale_f32 v141, s[2:3], v140, v140, v15
	v_rcp_f32_e32 v136, v135
	v_rcp_f32_e32 v142, v141
	v_fma_f32 v137, -v135, v136, 1.0
	v_fma_f32 v143, -v141, v142, 1.0
	v_fmac_f32_e32 v136, v137, v136
	v_fmac_f32_e32 v142, v143, v142
	v_div_scale_f32 v138, vcc, v31, v134, v31
	v_mul_f32_e32 v139, v138, v136
	v_fma_f32 v137, -v135, v139, v138
	v_fmac_f32_e32 v139, v137, v136
	v_fma_f32 v135, -v135, v139, v138
	v_div_fmas_f32 v135, v135, v136, v139
	v_div_scale_f32 v144, vcc, v15, v140, v15
	v_mul_f32_e32 v145, v144, v142
	v_fma_f32 v143, -v141, v145, v144
	v_fmac_f32_e32 v145, v143, v142
	v_fma_f32 v141, -v141, v145, v144
	v_div_fmas_f32 v141, v141, v142, v145
	v_div_fixup_f32 v134, v135, v134, v31
	v_div_fixup_f32 v140, v141, v140, v15
	v_bfe_u32 v135, v134, 16, 1
	v_bfe_u32 v141, v140, 16, 1
	v_add3_u32 v134, v134, v135, s1
	v_add3_u32 v140, v140, v141, s1
	ds_write_b16_d16_hi v147, v134 offset:7408
	ds_write_b16_d16_hi v147, v140 offset:7536
	s_waitcnt lgkmcnt(0)
	ds_read_b128 v[164:167], v148 offset:0
	ds_read_b128 v[168:171], v148 offset:1088
	ds_read_b128 v[172:175], v148 offset:2176
	ds_read_b128 v[224:227], v148 offset:3264
	ds_read_b128 v[228:231], v148 offset:4352
	ds_read_b128 v[232:235], v148 offset:5440
	ds_read_b128 v[236:239], v148 offset:6528
	ds_read_b128 v[240:243], v148 offset:7616
	s_waitcnt lgkmcnt(7)
	global_store_dwordx4 v[158:159], v[164:167], off
	v_lshl_add_u64 v[158:159], v[158:159], 0, s[100:101]
	s_waitcnt lgkmcnt(6)
	global_store_dwordx4 v[158:159], v[168:171], off
	v_lshl_add_u64 v[158:159], v[158:159], 0, s[100:101]
	s_waitcnt lgkmcnt(5)
	global_store_dwordx4 v[158:159], v[172:175], off
	v_lshl_add_u64 v[158:159], v[158:159], 0, s[100:101]
	s_waitcnt lgkmcnt(4)
	global_store_dwordx4 v[158:159], v[224:227], off
	v_lshl_add_u64 v[158:159], v[158:159], 0, s[100:101]
	s_waitcnt lgkmcnt(3)
	global_store_dwordx4 v[158:159], v[228:231], off
	v_lshl_add_u64 v[158:159], v[158:159], 0, s[100:101]
	s_waitcnt lgkmcnt(2)
	global_store_dwordx4 v[158:159], v[232:235], off
	v_lshl_add_u64 v[158:159], v[158:159], 0, s[100:101]
	s_waitcnt lgkmcnt(1)
	global_store_dwordx4 v[158:159], v[236:239], off
	v_lshl_add_u64 v[158:159], v[158:159], 0, s[100:101]
	s_waitcnt lgkmcnt(0)
	global_store_dwordx4 v[158:159], v[240:243], off
	v_lshl_add_u64 v[158:159], v[158:159], 0, s[100:101]
	s_mov_b64 s[2:3], 0
